# GU-tail weight conversion: bf16 stores carry the nt (streaming) hint like the f32 loads
# speedup vs baseline: 1.0048x; 1.0018x over previous
; __device__ __forceinline__ void conv_item(const float* W, int ldw, int Nout, int mode, const float* gk, unsigned char* dst, int item, int lane, LAS unsigned char* wl  ) {
;     const int nblk = Nout >> 8, k32 = item / nblk, nb0 = (item - k32 * nblk) * 256, nb = nb0 + lane * 4;
;     int sc = nb; if (mode == 1) sc = ((nb >> 7) & 1) * FF + (nb >> 8) * 128 + (nb & 127);
;     const float* src = W + (size_t)(k32 * 32) * ldw + sc;
;     f32x4 v[32];
; #pragma unroll
;     for (int i = 0; i < 32; ++i) v[i] = __builtin_nontemporal_load((const f32x4*)(src + (size_t)i * ldw));
;     if (gk) {
; #pragma unroll
;         for (int i = 0; i < 32; ++i) v[i] *= gk[k32 * 32 + i]; }
.LBB0_832:
	s_cmp_lt_i32 s13, 0
	s_cbranch_scc1 .LBB0_831
	s_and_b32 s6, s13, 0xffff
	s_mul_hi_u32 s7, s6, 0xaaaaaab
	s_mul_i32 s6, s6, 0xaaab
	s_mulk_i32 s7, 0x1800
	s_lshr_b32 s40, s6, 20
	s_sub_i32 s39, s38, s7
	s_mul_i32 s6, s40, 0xc0800
	v_subrev_u32_e32 v0, s7, v138
	s_add_u32 s6, s1, s6
	s_addc_u32 s7, s12, 0
	v_ashrrev_i32_e32 v1, 31, v0
	v_lshl_add_u64 v[60:61], v[0:1], 2, s[6:7]
	v_add_co_u32_e32 v0, vcc, s62, v60
	global_load_dwordx4 v[64:67], v[60:61], off nt
	s_nop 0
	v_addc_co_u32_e32 v1, vcc, 0, v61, vcc
	global_load_dwordx4 v[68:71], v[0:1], off offset:64 nt
	v_add_co_u32_e32 v0, vcc, s67, v60
	s_mov_b32 s6, 0x12000
	s_nop 0
	v_addc_co_u32_e32 v1, vcc, 0, v61, vcc
	global_load_dwordx4 v[72:75], v[0:1], off offset:128 nt
	v_add_co_u32_e32 v0, vcc, s6, v60
	s_mov_b32 s6, 0x18000
	s_nop 0
	v_addc_co_u32_e32 v1, vcc, 0, v61, vcc
	global_load_dwordx4 v[76:79], v[0:1], off offset:192 nt
	v_add_co_u32_e32 v0, vcc, s6, v60
	s_mov_b32 s6, 0x1e000
	s_nop 0
	v_addc_co_u32_e32 v1, vcc, 0, v61, vcc
	global_load_dwordx4 v[80:83], v[0:1], off offset:256 nt
	v_add_co_u32_e32 v0, vcc, s6, v60
	s_mov_b32 s6, 0x24000
	s_nop 0
	v_addc_co_u32_e32 v1, vcc, 0, v61, vcc
	global_load_dwordx4 v[84:87], v[0:1], off offset:320 nt
	v_add_co_u32_e32 v0, vcc, s6, v60
	s_mov_b32 s6, 0x2a000
	s_nop 0
	v_addc_co_u32_e32 v1, vcc, 0, v61, vcc
	global_load_dwordx4 v[88:91], v[0:1], off offset:384 nt
	v_add_co_u32_e32 v0, vcc, s6, v60
	s_mov_b32 s6, 0x30000
	s_nop 0
	v_addc_co_u32_e32 v1, vcc, 0, v61, vcc
	global_load_dwordx4 v[92:95], v[0:1], off offset:448 nt
	v_add_co_u32_e32 v0, vcc, s6, v60
	s_mov_b32 s6, 0x36000
	s_nop 0
	v_addc_co_u32_e32 v1, vcc, 0, v61, vcc
	global_load_dwordx4 v[96:99], v[0:1], off offset:512 nt
	v_add_co_u32_e32 v0, vcc, s6, v60
	s_mov_b32 s6, 0x3c000
	s_nop 0
	v_addc_co_u32_e32 v1, vcc, 0, v61, vcc
	global_load_dwordx4 v[100:103], v[0:1], off offset:576 nt
	v_add_co_u32_e32 v0, vcc, s6, v60
	s_mov_b32 s6, 0x42000
	s_nop 0
	v_addc_co_u32_e32 v1, vcc, 0, v61, vcc
	global_load_dwordx4 v[104:107], v[0:1], off offset:640 nt
	v_add_co_u32_e32 v0, vcc, s6, v60
	s_mov_b32 s6, 0x48000
	s_nop 0
	v_addc_co_u32_e32 v1, vcc, 0, v61, vcc
	global_load_dwordx4 v[108:111], v[0:1], off offset:704 nt
	v_add_co_u32_e32 v0, vcc, s6, v60
	s_mov_b32 s6, 0x4e000
	s_nop 0
	v_addc_co_u32_e32 v1, vcc, 0, v61, vcc
	global_load_dwordx4 v[112:115], v[0:1], off offset:768 nt
	v_add_co_u32_e32 v0, vcc, s6, v60
	s_mov_b32 s6, 0x54000
	s_nop 0
	v_addc_co_u32_e32 v1, vcc, 0, v61, vcc
	global_load_dwordx4 v[116:119], v[0:1], off offset:832 nt
	v_add_co_u32_e32 v0, vcc, s6, v60
	s_mov_b32 s6, 0x5a000
	s_nop 0
	v_addc_co_u32_e32 v1, vcc, 0, v61, vcc
	global_load_dwordx4 v[120:123], v[0:1], off offset:896 nt
	v_add_co_u32_e32 v0, vcc, s6, v60
	s_mov_b32 s6, 0x60000
	s_nop 0
	v_addc_co_u32_e32 v1, vcc, 0, v61, vcc
	global_load_dwordx4 v[124:127], v[0:1], off offset:960 nt
	v_add_co_u32_e32 v0, vcc, s6, v60
	s_mov_b32 s6, 0x66000
	s_nop 0
	v_addc_co_u32_e32 v1, vcc, 0, v61, vcc
	v_add_co_u32_e32 v4, vcc, s6, v60
	s_mov_b32 s6, 0x6c000
	s_nop 0
	v_addc_co_u32_e32 v5, vcc, 0, v61, vcc
	v_add_co_u32_e32 v8, vcc, s6, v60
	s_mov_b32 s6, 0x72000
	s_nop 0
	v_addc_co_u32_e32 v9, vcc, 0, v61, vcc
	v_add_co_u32_e32 v12, vcc, s6, v60
	s_mov_b32 s6, 0x78000
	s_nop 0
	v_addc_co_u32_e32 v13, vcc, 0, v61, vcc
	v_add_co_u32_e32 v16, vcc, s6, v60
	s_mov_b32 s6, 0x7e000
	s_nop 0
	v_addc_co_u32_e32 v17, vcc, 0, v61, vcc
	v_add_co_u32_e32 v20, vcc, s6, v60
	s_mov_b32 s6, 0x84000
	s_nop 0
	v_addc_co_u32_e32 v21, vcc, 0, v61, vcc
	v_add_co_u32_e32 v24, vcc, s6, v60
	s_mov_b32 s6, 0x8a000
	s_nop 0
	v_addc_co_u32_e32 v25, vcc, 0, v61, vcc
	v_add_co_u32_e32 v28, vcc, s6, v60
	s_mov_b32 s6, 0x90000
	s_nop 0
	v_addc_co_u32_e32 v29, vcc, 0, v61, vcc
	v_add_co_u32_e32 v32, vcc, s6, v60
	s_mov_b32 s6, 0x96000
	s_nop 0
	v_addc_co_u32_e32 v33, vcc, 0, v61, vcc
	v_add_co_u32_e32 v36, vcc, s6, v60
	s_mov_b32 s6, 0x9c000
	s_nop 0
	v_addc_co_u32_e32 v37, vcc, 0, v61, vcc
	v_add_co_u32_e32 v40, vcc, s6, v60
	s_mov_b32 s6, 0xa2000
	s_nop 0
	v_addc_co_u32_e32 v41, vcc, 0, v61, vcc
	v_add_co_u32_e32 v44, vcc, s6, v60
	s_mov_b32 s6, 0xa8000
	s_nop 0
	v_addc_co_u32_e32 v45, vcc, 0, v61, vcc
	v_add_co_u32_e32 v48, vcc, s6, v60
	s_mov_b32 s6, 0xae000
	s_nop 0
	v_addc_co_u32_e32 v49, vcc, 0, v61, vcc
	v_add_co_u32_e32 v52, vcc, s6, v60
	s_mov_b32 s6, 0xb4000
	s_nop 0
	v_addc_co_u32_e32 v53, vcc, 0, v61, vcc
	v_add_co_u32_e32 v56, vcc, s6, v60
	s_mov_b32 s6, 0xba000
	s_nop 0
	v_addc_co_u32_e32 v57, vcc, 0, v61, vcc
	v_add_co_u32_e32 v60, vcc, s6, v60
	s_lshl_b32 s6, s40, 7
	s_nop 0
	v_addc_co_u32_e32 v61, vcc, 0, v61, vcc
	v_mov_b32_e32 v165, s6
	global_load_dwordx4 v[0:3], v[0:1], off offset:1024 nt
	s_mulk_i32 s40, 0x1800
	global_load_dwordx4 v[4:7], v[4:5], off offset:1088 nt
	s_ashr_i32 s7, s39, 31
	global_load_dwordx4 v[8:11], v[8:9], off offset:1152 nt
	s_add_u32 s6, s40, s39
	global_load_dwordx4 v[12:15], v[12:13], off offset:1216 nt
	s_addc_u32 s7, 0, s7
	global_load_dwordx4 v[16:19], v[16:17], off offset:1280 nt
	s_lshl_b64 s[6:7], s[6:7], 6
	global_load_dwordx4 v[20:23], v[20:21], off offset:1344 nt
	s_nop 0
	global_load_dwordx4 v[24:27], v[24:25], off offset:1408 nt
	s_nop 0
	global_load_dwordx4 v[28:31], v[28:29], off offset:1472 nt
	s_nop 0
	global_load_dwordx4 v[32:35], v[32:33], off offset:1536 nt
	s_nop 0
	global_load_dwordx4 v[36:39], v[36:37], off offset:1600 nt
	s_nop 0
	global_load_dwordx4 v[40:43], v[40:41], off offset:1664 nt
	s_nop 0
	global_load_dwordx4 v[44:47], v[44:45], off offset:1728 nt
	s_nop 0
	global_load_dwordx4 v[48:51], v[48:49], off offset:1792 nt
	s_nop 0
	global_load_dwordx4 v[52:55], v[52:53], off offset:1856 nt
	s_nop 0
	global_load_dwordx4 v[56:59], v[56:57], off offset:1920 nt
	s_nop 0
	global_load_dwordx4 v[60:63], v[60:61], off offset:1984 nt
	s_nop 0
	global_load_dwordx4 v[166:169], v165, s[28:29] offset:48
	global_load_dwordx4 v[170:173], v165, s[28:29] offset:32
	global_load_dwordx4 v[158:161], v165, s[28:29] offset:16
	global_load_dwordx4 v[140:143], v165, s[28:29]
	s_waitcnt vmcnt(1)
; __device__ __forceinline__ void conv_item(const float* W, int ldw, int Nout, int mode, const float* gk, unsigned char* dst, int item, int lane, LAS unsigned char* wl  ) {
;     ...
;     if (gk) {
; #pragma unroll
;         for (int i = 0; i < 32; ++i) v[i] *= gk[k32 * 32 + i]; }
	v_pk_mul_f32 v[156:157], v[88:89], v[160:161] op_sel_hi:[1,0]
	s_waitcnt vmcnt(0)
	v_pk_mul_f32 v[146:147], v[64:65], v[140:141] op_sel_hi:[1,0]
	v_mov_b32_e32 v64, v143
	v_pk_mul_f32 v[130:131], v[66:67], v[140:141] op_sel_hi:[1,0]
	v_pk_mul_f32 v[134:135], v[70:71], v[140:141] op_sel:[0,1]
	v_pk_mul_f32 v[150:151], v[68:69], v[140:141] op_sel:[0,1]
	v_pk_mul_f32 v[140:141], v[78:79], v[64:65] op_sel_hi:[1,0]
	v_pk_mul_f32 v[154:155], v[76:77], v[64:65] op_sel_hi:[1,0]
	v_mov_b32_e32 v64, v161
	v_pk_mul_f32 v[132:133], v[74:75], v[142:143] op_sel_hi:[1,0]
	v_pk_mul_f32 v[148:149], v[72:73], v[142:143] op_sel_hi:[1,0]
	v_pk_mul_f32 v[142:143], v[86:87], v[158:159] op_sel:[0,1]
	v_pk_mul_f32 v[86:87], v[90:91], v[160:161] op_sel_hi:[1,0]
	v_pk_mul_f32 v[144:145], v[94:95], v[64:65] op_sel_hi:[1,0]
	v_pk_mul_f32 v[160:161], v[92:93], v[64:65] op_sel_hi:[1,0]
	v_mov_b32_e32 v64, v173
	v_pk_mul_f32 v[136:137], v[82:83], v[158:159] op_sel_hi:[1,0]
	v_pk_mul_f32 v[82:83], v[106:107], v[172:173] op_sel_hi:[1,0]
	v_pk_mul_f32 v[90:91], v[110:111], v[64:65] op_sel_hi:[1,0]
	v_pk_mul_f32 v[106:107], v[108:109], v[64:65] op_sel_hi:[1,0]
	v_mov_b32_e32 v64, v169
	v_pk_mul_f32 v[152:153], v[80:81], v[158:159] op_sel_hi:[1,0]
	v_pk_mul_f32 v[158:159], v[84:85], v[158:159] op_sel:[0,1]
	v_pk_mul_f32 v[80:81], v[98:99], v[170:171] op_sel_hi:[1,0]
	v_pk_mul_f32 v[98:99], v[96:97], v[170:171] op_sel_hi:[1,0]
	v_pk_mul_f32 v[84:85], v[102:103], v[170:171] op_sel:[0,1]
	v_pk_mul_f32 v[102:103], v[100:101], v[170:171] op_sel:[0,1]
	v_pk_mul_f32 v[100:101], v[104:105], v[172:173] op_sel_hi:[1,0]
	v_pk_mul_f32 v[104:105], v[112:113], v[166:167] op_sel_hi:[1,0]
	v_pk_mul_f32 v[96:97], v[126:127], v[64:65] op_sel_hi:[1,0]
	v_pk_mul_f32 v[112:113], v[124:125], v[64:65] op_sel_hi:[1,0]
	global_load_dwordx4 v[64:67], v165, s[28:29] offset:112
	global_load_dwordx4 v[68:71], v165, s[28:29] offset:96
	global_load_dwordx4 v[72:75], v165, s[28:29] offset:80
	global_load_dwordx4 v[76:79], v165, s[28:29] offset:64
	v_pk_mul_f32 v[110:111], v[116:117], v[166:167] op_sel:[0,1]
	v_pk_mul_f32 v[88:89], v[114:115], v[166:167] op_sel_hi:[1,0]
	v_pk_mul_f32 v[92:93], v[122:123], v[168:169] op_sel_hi:[1,0]
	v_pk_mul_f32 v[94:95], v[118:119], v[166:167] op_sel:[0,1]
	v_pk_mul_f32 v[108:109], v[120:121], v[168:169] op_sel_hi:[1,0]
	s_waitcnt vmcnt(2)
	v_pk_mul_f32 v[122:123], v[32:33], v[68:69] op_sel_hi:[1,0]
	v_mov_b32_e32 v32, v67
	s_waitcnt vmcnt(0)
; #define LAS __attribute__((address_space(3)))
; __device__ __forceinline__ unsigned cvt_pk_bf16(float lo, float hi) { unsigned r; asm volatile("v_cvt_pk_bf16_f32 %0, %1, %2" : "=v"(r) : "v"(lo), "v"(hi)); return r; }
; __device__ __forceinline__ void conv_item(const float* W, int ldw, int Nout, int mode, const float* gk, unsigned char* dst, int item, int lane, LAS unsigned char* wl  ) {
;     ...
;     LAS unsigned char* mine = wl + lane * 272;
; #pragma unroll
;     for (int j = 0; j < 4; ++j)
; #pragma unroll
;         for (int q = 0; q < 4; ++q) { u32x4 w;
;             w.x = cvt_pk_bf16(v[8 * q + 0][j], v[8 * q + 1][j]); w.y = cvt_pk_bf16(v[8 * q + 2][j], v[8 * q + 3][j]);
;             w.z = cvt_pk_bf16(v[8 * q + 4][j], v[8 * q + 5][j]); w.w = cvt_pk_bf16(v[8 * q + 6][j], v[8 * q + 7][j]);
;             *(LAS u32x4*)(mine + (j * 4 + q) * 16) = w; }
;     asm volatile("s_waitcnt lgkmcnt(0)" ::: "memory");
;     unsigned char* d = dst + ((size_t)k32 * Nout + nb0) * 64 + lane * 16;
;     const LAS unsigned char* rd = wl + (lane >> 4) * 272 + (lane & 15) * 16;
; #pragma unroll
;     for (int s = 0; s < 16; ++s) { const u32x4 w = *(const LAS u32x4*)(rd + s * 4 * 272); *(u32x4*)(d + s * 1024) = w; }
;     asm volatile("s_waitcnt lgkmcnt(0)" ::: "memory");
	v_pk_mul_f32 v[116:117], v[8:9], v[78:79] op_sel_hi:[1,0]
	v_mov_b32_e32 v8, v79
	v_pk_mul_f32 v[114:115], v[0:1], v[76:77] op_sel_hi:[1,0]
	v_pk_mul_f32 v[0:1], v[6:7], v[76:77] op_sel:[0,1]
	v_pk_mul_f32 v[6:7], v[14:15], v[8:9] op_sel_hi:[1,0]
	v_mov_b32_e32 v14, v75
	v_pk_mul_f32 v[2:3], v[2:3], v[76:77] op_sel_hi:[1,0]
	v_pk_mul_f32 v[76:77], v[4:5], v[76:77] op_sel:[0,1]
	v_pk_mul_f32 v[4:5], v[10:11], v[78:79] op_sel_hi:[1,0]
	v_pk_mul_f32 v[78:79], v[12:13], v[8:9] op_sel_hi:[1,0]
	v_pk_mul_f32 v[8:9], v[18:19], v[72:73] op_sel_hi:[1,0]
	v_pk_mul_f32 v[118:119], v[16:17], v[72:73] op_sel_hi:[1,0]
	v_pk_mul_f32 v[10:11], v[22:23], v[72:73] op_sel:[0,1]
	v_pk_mul_f32 v[72:73], v[20:21], v[72:73] op_sel:[0,1]
	v_pk_mul_f32 v[12:13], v[26:27], v[74:75] op_sel_hi:[1,0]
	v_pk_mul_f32 v[120:121], v[24:25], v[74:75] op_sel_hi:[1,0]
	v_pk_mul_f32 v[16:17], v[30:31], v[14:15] op_sel_hi:[1,0]
	v_pk_mul_f32 v[74:75], v[28:29], v[14:15] op_sel_hi:[1,0]
	v_pk_mul_f32 v[14:15], v[34:35], v[68:69] op_sel_hi:[1,0]
	v_pk_mul_f32 v[20:21], v[42:43], v[70:71] op_sel_hi:[1,0]
	v_pk_mul_f32 v[42:43], v[48:49], v[64:65] op_sel_hi:[1,0]
	v_pk_mul_f32 v[30:31], v[62:63], v[32:33] op_sel_hi:[1,0]
	v_pk_mul_f32 v[48:49], v[60:61], v[32:33] op_sel_hi:[1,0]
	v_cvt_pk_bf16_f32 v32, v146, v150
	v_cvt_pk_bf16_f32 v33, v148, v154
	v_cvt_pk_bf16_f32 v34, v152, v158
	v_cvt_pk_bf16_f32 v35, v156, v160
	ds_write_b128 v163, v[32:35]
	v_cvt_pk_bf16_f32 v32, v98, v102
	v_cvt_pk_bf16_f32 v33, v100, v106
	v_cvt_pk_bf16_f32 v34, v104, v110
	v_cvt_pk_bf16_f32 v35, v108, v112
	v_mov_b32_e32 v24, v71
	ds_write_b128 v163, v[32:35] offset:16
	v_cvt_pk_bf16_f32 v32, v114, v76
	v_cvt_pk_bf16_f32 v33, v116, v78
	v_cvt_pk_bf16_f32 v34, v118, v72
	v_cvt_pk_bf16_f32 v35, v120, v74
	v_pk_mul_f32 v[18:19], v[38:39], v[68:69] op_sel:[0,1]
	v_pk_mul_f32 v[36:37], v[36:37], v[68:69] op_sel:[0,1]
	v_pk_mul_f32 v[38:39], v[40:41], v[70:71] op_sel_hi:[1,0]
	v_pk_mul_f32 v[22:23], v[46:47], v[24:25] op_sel_hi:[1,0]
	v_pk_mul_f32 v[40:41], v[44:45], v[24:25] op_sel_hi:[1,0]
	v_pk_mul_f32 v[44:45], v[52:53], v[64:65] op_sel:[0,1]
	v_pk_mul_f32 v[46:47], v[56:57], v[66:67] op_sel_hi:[1,0]
	ds_write_b128 v163, v[32:35] offset:32
	v_cvt_pk_bf16_f32 v32, v122, v36
	v_cvt_pk_bf16_f32 v33, v38, v40
	v_cvt_pk_bf16_f32 v34, v42, v44
	v_cvt_pk_bf16_f32 v35, v46, v48
	ds_write_b128 v163, v[32:35] offset:48
	v_cvt_pk_bf16_f32 v32, v147, v151
	v_cvt_pk_bf16_f32 v33, v149, v155
	v_cvt_pk_bf16_f32 v34, v153, v159
	v_cvt_pk_bf16_f32 v35, v157, v161
	ds_write_b128 v163, v[32:35] offset:64
	v_cvt_pk_bf16_f32 v32, v99, v103
	v_cvt_pk_bf16_f32 v33, v101, v107
	v_cvt_pk_bf16_f32 v34, v105, v111
	v_cvt_pk_bf16_f32 v35, v109, v113
	ds_write_b128 v163, v[32:35] offset:80
	v_cvt_pk_bf16_f32 v32, v115, v77
	v_cvt_pk_bf16_f32 v33, v117, v79
	v_cvt_pk_bf16_f32 v34, v119, v73
	v_cvt_pk_bf16_f32 v35, v121, v75
	ds_write_b128 v163, v[32:35] offset:96
	v_cvt_pk_bf16_f32 v32, v123, v37
	v_cvt_pk_bf16_f32 v33, v39, v41
	v_cvt_pk_bf16_f32 v34, v43, v45
	v_cvt_pk_bf16_f32 v35, v47, v49
	ds_write_b128 v163, v[32:35] offset:112
	v_cvt_pk_bf16_f32 v32, v130, v134
	v_cvt_pk_bf16_f32 v33, v132, v140
	v_cvt_pk_bf16_f32 v34, v136, v142
	v_cvt_pk_bf16_f32 v35, v86, v144
	ds_write_b128 v163, v[32:35] offset:128
	v_cvt_pk_bf16_f32 v32, v80, v84
	v_cvt_pk_bf16_f32 v33, v82, v90
	v_cvt_pk_bf16_f32 v34, v88, v94
	v_cvt_pk_bf16_f32 v35, v92, v96
	ds_write_b128 v163, v[32:35] offset:144
	v_cvt_pk_bf16_f32 v32, v2, v0
	v_cvt_pk_bf16_f32 v33, v4, v6
	v_cvt_pk_bf16_f32 v34, v8, v10
	v_cvt_pk_bf16_f32 v35, v12, v16
	v_pk_mul_f32 v[24:25], v[50:51], v[64:65] op_sel_hi:[1,0]
	v_pk_mul_f32 v[26:27], v[54:55], v[64:65] op_sel:[0,1]
	v_pk_mul_f32 v[28:29], v[58:59], v[66:67] op_sel_hi:[1,0]
	ds_write_b128 v163, v[32:35] offset:160
	v_cvt_pk_bf16_f32 v32, v14, v18
	v_cvt_pk_bf16_f32 v33, v20, v22
	v_cvt_pk_bf16_f32 v34, v24, v26
	v_cvt_pk_bf16_f32 v35, v28, v30
	ds_write_b128 v163, v[32:35] offset:176
	v_cvt_pk_bf16_f32 v32, v131, v135
	v_cvt_pk_bf16_f32 v33, v133, v141
	v_cvt_pk_bf16_f32 v34, v137, v143
	v_cvt_pk_bf16_f32 v35, v87, v145
	ds_write_b128 v163, v[32:35] offset:192
	v_cvt_pk_bf16_f32 v32, v81, v85
	v_cvt_pk_bf16_f32 v33, v83, v91
	v_cvt_pk_bf16_f32 v34, v89, v95
	v_cvt_pk_bf16_f32 v35, v93, v97
	ds_write_b128 v163, v[32:35] offset:208
	v_cvt_pk_bf16_f32 v0, v3, v1
	v_cvt_pk_bf16_f32 v1, v5, v7
	v_cvt_pk_bf16_f32 v2, v9, v11
	v_cvt_pk_bf16_f32 v3, v13, v17
	ds_write_b128 v163, v[0:3] offset:224
	v_cvt_pk_bf16_f32 v0, v15, v19
	v_cvt_pk_bf16_f32 v1, v21, v23
	v_cvt_pk_bf16_f32 v2, v25, v27
	v_cvt_pk_bf16_f32 v3, v29, v31
	ds_write_b128 v163, v[0:3] offset:240
	s_waitcnt lgkmcnt(0)
	ds_read_b128 v[0:3], v164
	v_lshl_add_u64 v[4:5], v[128:129], 0, s[6:7]
	v_add_co_u32_e32 v6, vcc, s34, v4
	s_waitcnt lgkmcnt(0)
	global_store_dwordx4 v[4:5], v[0:3], off nt
	ds_read_b128 v[0:3], v164 offset:1088
	v_addc_co_u32_e32 v7, vcc, 0, v5, vcc
	v_add_co_u32_e32 v8, vcc, s60, v4
	s_waitcnt lgkmcnt(0)
	global_store_dwordx4 v[4:5], v[0:3], off offset:1024 nt
	ds_read_b128 v[0:3], v164 offset:2176
	v_addc_co_u32_e32 v9, vcc, 0, v5, vcc
	s_waitcnt lgkmcnt(0)
	global_store_dwordx4 v[4:5], v[0:3], off offset:2048 nt
	ds_read_b128 v[0:3], v164 offset:3264
	s_waitcnt lgkmcnt(0)
	global_store_dwordx4 v[4:5], v[0:3], off offset:3072 nt
	ds_read_b128 v[0:3], v164 offset:4352
	v_add_co_u32_e32 v4, vcc, 0x3000, v4
	s_waitcnt lgkmcnt(0)
	global_store_dwordx4 v[8:9], v[0:3], off offset:-4096 nt
	ds_read_b128 v[0:3], v164 offset:5440
	v_addc_co_u32_e32 v5, vcc, 0, v5, vcc
	s_waitcnt lgkmcnt(0)
	global_store_dwordx4 v[6:7], v[0:3], off offset:1024 nt
	ds_read_b128 v[0:3], v164 offset:6528
	s_waitcnt lgkmcnt(0)
	global_store_dwordx4 v[6:7], v[0:3], off offset:2048 nt
	ds_read_b128 v[0:3], v164 offset:7616
	s_waitcnt lgkmcnt(0)
	global_store_dwordx4 v[6:7], v[0:3], off offset:3072 nt
	ds_read_b128 v[0:3], v164 offset:8704
	s_waitcnt lgkmcnt(0)
	global_store_dwordx4 v[8:9], v[0:3], off nt
	ds_read_b128 v[0:3], v164 offset:9792
	s_waitcnt lgkmcnt(0)
	global_store_dwordx4 v[8:9], v[0:3], off offset:1024 nt
	ds_read_b128 v[0:3], v164 offset:10880
	s_waitcnt lgkmcnt(0)
	global_store_dwordx4 v[8:9], v[0:3], off offset:2048 nt
	ds_read_b128 v[0:3], v164 offset:11968
	s_waitcnt lgkmcnt(0)
	global_store_dwordx4 v[8:9], v[0:3], off offset:3072 nt
	ds_read_b128 v[0:3], v164 offset:13056
	s_waitcnt lgkmcnt(0)
	global_store_dwordx4 v[4:5], v[0:3], off nt
	ds_read_b128 v[0:3], v164 offset:14144
	s_waitcnt lgkmcnt(0)
	global_store_dwordx4 v[4:5], v[0:3], off offset:1024 nt
	ds_read_b128 v[0:3], v164 offset:15232
	s_waitcnt lgkmcnt(0)
	global_store_dwordx4 v[4:5], v[0:3], off offset:2048 nt
	ds_read_b128 v[0:3], v164 offset:16320
	s_waitcnt lgkmcnt(0)
	global_store_dwordx4 v[4:5], v[0:3], off offset:3072 nt
	s_waitcnt lgkmcnt(0)
	s_branch .LBB0_831

; #define LAS __attribute__((address_space(3)))
; __device__ __forceinline__ unsigned cvt_pk_bf16(float lo, float hi) { unsigned r; asm volatile("v_cvt_pk_bf16_f32 %0, %1, %2" : "=v"(r) : "v"(lo), "v"(hi)); return r; }
; __device__ __forceinline__ void conv_item(const float* W, int ldw, int Nout, int mode, const float* gk, unsigned char* dst, int item, int lane, LAS unsigned char* wl  ) {
;     const int nblk = Nout >> 8, k32 = item / nblk, nb0 = (item - k32 * nblk) * 256, nb = nb0 + lane * 4;
;     int sc = nb; if (mode == 1) sc = ((nb >> 7) & 1) * FF + (nb >> 8) * 128 + (nb & 127);
;     const float* src = W + (size_t)(k32 * 32) * ldw + sc;
;     f32x4 v[32];
; #pragma unroll
;     for (int i = 0; i < 32; ++i) v[i] = __builtin_nontemporal_load((const f32x4*)(src + (size_t)i * ldw));
;     if (gk) {
; #pragma unroll
;         for (int i = 0; i < 32; ++i) v[i] *= gk[k32 * 32 + i]; }
;     LAS unsigned char* mine = wl + lane * 272;
; #pragma unroll
;     for (int j = 0; j < 4; ++j)
; #pragma unroll
;         for (int q = 0; q < 4; ++q) { u32x4 w;
;             w.x = cvt_pk_bf16(v[8 * q + 0][j], v[8 * q + 1][j]); w.y = cvt_pk_bf16(v[8 * q + 2][j], v[8 * q + 3][j]);
;             w.z = cvt_pk_bf16(v[8 * q + 4][j], v[8 * q + 5][j]); w.w = cvt_pk_bf16(v[8 * q + 6][j], v[8 * q + 7][j]);
;             *(LAS u32x4*)(mine + (j * 4 + q) * 16) = w; }
.LBB0_840:
	s_add_i32 s6, s42, s1
	s_cmp_ge_u32 s6, s0
	s_cbranch_scc1 .LBB0_839
	s_lshr_b32 s6, s1, 31
	s_add_i32 s6, s1, s6
	s_ashr_i32 s28, s6, 1
	s_lshl_b32 s6, s28, 9
	s_sub_i32 s38, s47, s6
	s_lshl_b32 s6, s28, 5
	s_ashr_i32 s7, s6, 31
	s_lshl_b64 s[6:7], s[6:7], 11
	v_add_u32_e32 v0, s38, v128
	s_add_u32 s6, s43, s6
	s_addc_u32 s7, s44, s7
	v_ashrrev_i32_e32 v1, 31, v0
	v_lshl_add_u64 v[116:117], v[0:1], 2, s[6:7]
	v_add_co_u32_e32 v20, vcc, s34, v116
	s_movk_i32 s6, 0x3000
	s_nop 0
	v_addc_co_u32_e32 v21, vcc, 0, v117, vcc
	v_add_co_u32_e32 v16, vcc, s60, v116
	global_load_dwordx4 v[0:3], v[116:117], off nt
	global_load_dwordx4 v[4:7], v[116:117], off offset:2048 nt
	v_addc_co_u32_e32 v17, vcc, 0, v117, vcc
	v_add_co_u32_e32 v22, vcc, s6, v116
	s_movk_i32 s6, 0x5000
	s_nop 0
	v_addc_co_u32_e32 v23, vcc, 0, v117, vcc
	v_add_co_u32_e32 v36, vcc, s26, v116
	global_load_dwordx4 v[12:15], v[16:17], off offset:-4096 nt
	global_load_dwordx4 v[8:11], v[16:17], off nt
	s_nop 0
	global_load_dwordx4 v[16:19], v[16:17], off offset:2048 nt
	v_addc_co_u32_e32 v37, vcc, 0, v117, vcc
	v_add_co_u32_e32 v52, vcc, s6, v116
	s_movk_i32 s6, 0x7000
	s_nop 0
	v_addc_co_u32_e32 v53, vcc, 0, v117, vcc
	v_add_co_u32_e32 v48, vcc, s62, v116
	global_load_dwordx4 v[32:35], v[20:21], off offset:2048 nt
	global_load_dwordx4 v[24:27], v[22:23], off offset:2048 nt
	global_load_dwordx4 v[28:31], v[36:37], off offset:-4096 nt
	s_nop 0
	global_load_dwordx4 v[20:23], v[36:37], off nt
	v_addc_co_u32_e32 v49, vcc, 0, v117, vcc
	v_add_co_u32_e32 v54, vcc, s6, v116
	s_mov_b32 s6, 0x9000
	s_nop 0
	v_addc_co_u32_e32 v55, vcc, 0, v117, vcc
	v_add_co_u32_e32 v68, vcc, s27, v116
	global_load_dwordx4 v[40:43], v[36:37], off offset:2048 nt
	global_load_dwordx4 v[44:47], v[48:49], off offset:-4096 nt
	s_nop 0
	global_load_dwordx4 v[36:39], v[48:49], off nt
	s_nop 0
	global_load_dwordx4 v[48:51], v[48:49], off offset:2048 nt
	v_addc_co_u32_e32 v69, vcc, 0, v117, vcc
	v_add_co_u32_e32 v84, vcc, s6, v116
	s_mov_b32 s6, 0xd000
	s_nop 0
	v_addc_co_u32_e32 v85, vcc, 0, v117, vcc
	v_add_co_u32_e32 v80, vcc, s64, v116
	global_load_dwordx4 v[64:67], v[52:53], off offset:2048 nt
	global_load_dwordx4 v[56:59], v[54:55], off offset:2048 nt
	global_load_dwordx4 v[60:63], v[68:69], off offset:-4096 nt
	s_nop 0
	global_load_dwordx4 v[52:55], v[68:69], off nt
	v_addc_co_u32_e32 v81, vcc, 0, v117, vcc
	v_add_co_u32_e32 v86, vcc, s56, v116
	global_load_dwordx4 v[72:75], v[68:69], off offset:2048 nt
	global_load_dwordx4 v[76:79], v[80:81], off offset:-4096 nt
	s_nop 0
	global_load_dwordx4 v[68:71], v[80:81], off nt
	s_nop 0
	global_load_dwordx4 v[80:83], v[80:81], off offset:2048 nt
	v_addc_co_u32_e32 v87, vcc, 0, v117, vcc
	v_add_co_u32_e32 v100, vcc, s67, v116
	s_ashr_i32 s29, s28, 31
	s_nop 0
	v_addc_co_u32_e32 v101, vcc, 0, v117, vcc
	v_add_co_u32_e32 v118, vcc, s6, v116
	s_mov_b32 s6, 0xf000
	s_nop 0
	v_addc_co_u32_e32 v119, vcc, 0, v117, vcc
	v_add_co_u32_e32 v112, vcc, s11, v116
	global_load_dwordx4 v[96:99], v[84:85], off offset:2048 nt
	global_load_dwordx4 v[88:91], v[86:87], off offset:2048 nt
	global_load_dwordx4 v[92:95], v[100:101], off offset:-4096 nt
	s_nop 0
	global_load_dwordx4 v[84:87], v[100:101], off nt
	v_addc_co_u32_e32 v113, vcc, 0, v117, vcc
	v_add_co_u32_e32 v120, vcc, s6, v116
	global_load_dwordx4 v[104:107], v[100:101], off offset:2048 nt
	global_load_dwordx4 v[108:111], v[112:113], off offset:-4096 nt
	s_nop 0
	global_load_dwordx4 v[100:103], v[112:113], off nt
	s_nop 0
	global_load_dwordx4 v[112:115], v[112:113], off offset:2048 nt
	v_addc_co_u32_e32 v121, vcc, 0, v117, vcc
	global_load_dwordx4 v[124:127], v[118:119], off offset:2048 nt
	s_nop 0
	global_load_dwordx4 v[116:119], v[120:121], off nt
	s_nop 0
	global_load_dwordx4 v[120:123], v[120:121], off offset:2048 nt
	s_ashr_i32 s39, s38, 31
	s_waitcnt vmcnt(30)
	v_cvt_pk_bf16_f32 v132, v0, v4
	s_waitcnt vmcnt(26)
	v_cvt_pk_bf16_f32 v133, v12, v32
	v_cvt_pk_bf16_f32 v134, v8, v16
	s_waitcnt vmcnt(24)
	v_cvt_pk_bf16_f32 v135, v28, v24
	ds_write_b128 v129, v[132:135]
	s_waitcnt vmcnt(22)
	v_cvt_pk_bf16_f32 v132, v20, v40
	s_waitcnt vmcnt(18)
	v_cvt_pk_bf16_f32 v133, v44, v64
	v_cvt_pk_bf16_f32 v134, v36, v48
	s_waitcnt vmcnt(16)
	v_cvt_pk_bf16_f32 v135, v60, v56
	ds_write_b128 v129, v[132:135] offset:16
	s_waitcnt vmcnt(14)
	v_cvt_pk_bf16_f32 v132, v52, v72
	s_waitcnt vmcnt(10)
	v_cvt_pk_bf16_f32 v133, v76, v96
	v_cvt_pk_bf16_f32 v134, v68, v80
	s_waitcnt vmcnt(8)
	v_cvt_pk_bf16_f32 v135, v92, v88
	ds_write_b128 v129, v[132:135] offset:32
	s_waitcnt vmcnt(6)
	v_cvt_pk_bf16_f32 v132, v84, v104
	s_waitcnt vmcnt(2)
	v_cvt_pk_bf16_f32 v133, v108, v124
	v_cvt_pk_bf16_f32 v134, v100, v112
	s_waitcnt vmcnt(0)
; #define LAS __attribute__((address_space(3)))
; __device__ __forceinline__ unsigned cvt_pk_bf16(float lo, float hi) { unsigned r; asm volatile("v_cvt_pk_bf16_f32 %0, %1, %2" : "=v"(r) : "v"(lo), "v"(hi)); return r; }
; __device__ __forceinline__ void conv_item(const float* W, int ldw, int Nout, int mode, const float* gk, unsigned char* dst, int item, int lane, LAS unsigned char* wl  ) {
;     ...
;         for (int q = 0; q < 4; ++q) { u32x4 w;
;             w.x = cvt_pk_bf16(v[8 * q + 0][j], v[8 * q + 1][j]); w.y = cvt_pk_bf16(v[8 * q + 2][j], v[8 * q + 3][j]);
;             w.z = cvt_pk_bf16(v[8 * q + 4][j], v[8 * q + 5][j]); w.w = cvt_pk_bf16(v[8 * q + 6][j], v[8 * q + 7][j]);
;             *(LAS u32x4*)(mine + (j * 4 + q) * 16) = w; }
;     asm volatile("s_waitcnt lgkmcnt(0)" ::: "memory");
;     unsigned char* d = dst + ((size_t)k32 * Nout + nb0) * 64 + lane * 16;
;     const LAS unsigned char* rd = wl + (lane >> 4) * 272 + (lane & 15) * 16;
; #pragma unroll
;     for (int s = 0; s < 16; ++s) { const u32x4 w = *(const LAS u32x4*)(rd + s * 4 * 272); *(u32x4*)(d + s * 1024) = w; }
;     asm volatile("s_waitcnt lgkmcnt(0)" ::: "memory");
	v_cvt_pk_bf16_f32 v135, v116, v120
	ds_write_b128 v129, v[132:135] offset:48
	v_cvt_pk_bf16_f32 v132, v1, v5
	v_cvt_pk_bf16_f32 v133, v13, v33
	v_cvt_pk_bf16_f32 v134, v9, v17
	v_cvt_pk_bf16_f32 v135, v29, v25
	ds_write_b128 v129, v[132:135] offset:64
	v_cvt_pk_bf16_f32 v132, v21, v41
	v_cvt_pk_bf16_f32 v133, v45, v65
	v_cvt_pk_bf16_f32 v134, v37, v49
	v_cvt_pk_bf16_f32 v135, v61, v57
	ds_write_b128 v129, v[132:135] offset:80
	v_cvt_pk_bf16_f32 v132, v53, v73
	v_cvt_pk_bf16_f32 v133, v77, v97
	v_cvt_pk_bf16_f32 v134, v69, v81
	v_cvt_pk_bf16_f32 v135, v93, v89
	ds_write_b128 v129, v[132:135] offset:96
	v_cvt_pk_bf16_f32 v132, v85, v105
	v_cvt_pk_bf16_f32 v133, v109, v125
	v_cvt_pk_bf16_f32 v134, v101, v113
	v_cvt_pk_bf16_f32 v135, v117, v121
	ds_write_b128 v129, v[132:135] offset:112
	v_cvt_pk_bf16_f32 v132, v2, v6
	v_cvt_pk_bf16_f32 v133, v14, v34
	v_cvt_pk_bf16_f32 v134, v10, v18
	v_cvt_pk_bf16_f32 v135, v30, v26
	ds_write_b128 v129, v[132:135] offset:128
	v_cvt_pk_bf16_f32 v132, v22, v42
	v_cvt_pk_bf16_f32 v133, v46, v66
	v_cvt_pk_bf16_f32 v134, v38, v50
	v_cvt_pk_bf16_f32 v135, v62, v58
	ds_write_b128 v129, v[132:135] offset:144
	v_cvt_pk_bf16_f32 v132, v54, v74
	v_cvt_pk_bf16_f32 v133, v78, v98
	v_cvt_pk_bf16_f32 v134, v70, v82
	v_cvt_pk_bf16_f32 v135, v94, v90
	ds_write_b128 v129, v[132:135] offset:160
	v_cvt_pk_bf16_f32 v132, v86, v106
	v_cvt_pk_bf16_f32 v133, v110, v126
	v_cvt_pk_bf16_f32 v134, v102, v114
	v_cvt_pk_bf16_f32 v135, v118, v122
	ds_write_b128 v129, v[132:135] offset:176
	v_cvt_pk_bf16_f32 v0, v3, v7
	v_cvt_pk_bf16_f32 v1, v15, v35
	v_cvt_pk_bf16_f32 v2, v11, v19
	v_cvt_pk_bf16_f32 v3, v31, v27
	ds_write_b128 v129, v[0:3] offset:192
	v_cvt_pk_bf16_f32 v0, v23, v43
	v_cvt_pk_bf16_f32 v1, v47, v67
	v_cvt_pk_bf16_f32 v2, v39, v51
	v_cvt_pk_bf16_f32 v3, v63, v59
	ds_write_b128 v129, v[0:3] offset:208
	v_cvt_pk_bf16_f32 v0, v55, v75
	v_cvt_pk_bf16_f32 v1, v79, v99
	v_cvt_pk_bf16_f32 v2, v71, v83
	v_cvt_pk_bf16_f32 v3, v95, v91
	ds_write_b128 v129, v[0:3] offset:224
	v_cvt_pk_bf16_f32 v0, v87, v107
	v_cvt_pk_bf16_f32 v1, v111, v127
	v_cvt_pk_bf16_f32 v2, v103, v115
	v_cvt_pk_bf16_f32 v3, v119, v123
	ds_write_b128 v129, v[0:3] offset:240
	s_waitcnt lgkmcnt(0)
	s_lshl_b64 s[6:7], s[28:29], 15
	s_lshl_b64 s[28:29], s[38:39], 6
	s_add_u32 s6, s45, s6
	ds_read_b128 v[0:3], v130
	ds_read_b128 v[4:7], v130 offset:1088
	ds_read_b128 v[8:11], v130 offset:2176
	ds_read_b128 v[12:15], v130 offset:3264
	s_addc_u32 s7, s46, s7
	s_add_u32 s6, s6, s28
	s_addc_u32 s7, s7, s29
	v_lshl_add_u64 v[20:21], s[6:7], 0, v[138:139]
	s_waitcnt lgkmcnt(3)
	global_store_dwordx4 v[20:21], v[0:3], off nt
	s_waitcnt lgkmcnt(2)
	global_store_dwordx4 v[20:21], v[4:7], off offset:1024 nt
	s_waitcnt lgkmcnt(1)
	global_store_dwordx4 v[20:21], v[8:11], off offset:2048 nt
	s_waitcnt lgkmcnt(0)
	global_store_dwordx4 v[20:21], v[12:15], off offset:3072 nt
	ds_read_b128 v[0:3], v130 offset:4352
	ds_read_b128 v[4:7], v130 offset:5440
	ds_read_b128 v[8:11], v130 offset:6528
	v_add_co_u32_e32 v22, vcc, s34, v20
	s_nop 1
	v_addc_co_u32_e32 v23, vcc, 0, v21, vcc
	v_add_co_u32_e32 v24, vcc, s60, v20
	s_nop 1
	v_addc_co_u32_e32 v25, vcc, 0, v21, vcc
	s_waitcnt lgkmcnt(2)
	global_store_dwordx4 v[24:25], v[0:3], off offset:-4096 nt
	s_waitcnt lgkmcnt(1)
	global_store_dwordx4 v[22:23], v[4:7], off offset:1024 nt
	s_waitcnt lgkmcnt(0)
	global_store_dwordx4 v[22:23], v[8:11], off offset:2048 nt
	ds_read_b128 v[0:3], v130 offset:7616
	ds_read_b128 v[4:7], v130 offset:8704
	ds_read_b128 v[8:11], v130 offset:9792
	ds_read_b128 v[12:15], v130 offset:10880
	ds_read_b128 v[16:19], v130 offset:11968
	s_waitcnt lgkmcnt(4)
	global_store_dwordx4 v[22:23], v[0:3], off offset:3072 nt
	s_waitcnt lgkmcnt(3)
	global_store_dwordx4 v[24:25], v[4:7], off nt
	s_waitcnt lgkmcnt(2)
	global_store_dwordx4 v[24:25], v[8:11], off offset:1024 nt
	s_waitcnt lgkmcnt(1)
	global_store_dwordx4 v[24:25], v[12:15], off offset:2048 nt
	s_waitcnt lgkmcnt(0)
	global_store_dwordx4 v[24:25], v[16:19], off offset:3072 nt
	ds_read_b128 v[0:3], v130 offset:13056
	ds_read_b128 v[4:7], v130 offset:14144
	ds_read_b128 v[8:11], v130 offset:15232
	ds_read_b128 v[12:15], v130 offset:16320
	v_add_co_u32_e32 v16, vcc, 0x3000, v20
	s_nop 1
	v_addc_co_u32_e32 v17, vcc, 0, v21, vcc
	s_waitcnt lgkmcnt(3)
	global_store_dwordx4 v[16:17], v[0:3], off nt
	s_waitcnt lgkmcnt(2)
	global_store_dwordx4 v[16:17], v[4:7], off offset:1024 nt
	s_waitcnt lgkmcnt(1)
	global_store_dwordx4 v[16:17], v[8:11], off offset:2048 nt
	s_waitcnt lgkmcnt(0)
	global_store_dwordx4 v[16:17], v[12:15], off offset:3072 nt
	s_waitcnt lgkmcnt(0)
	s_branch .LBB0_839

; __device__ __forceinline__ void conv_item(const float* W, int ldw, int Nout, int mode, const float* gk, unsigned char* dst, int item, int lane, LAS unsigned char* wl  ) {
;     const int nblk = Nout >> 8, k32 = item / nblk, nb0 = (item - k32 * nblk) * 256, nb = nb0 + lane * 4;
;     int sc = nb; if (mode == 1) sc = ((nb >> 7) & 1) * FF + (nb >> 8) * 128 + (nb & 127);
;     const float* src = W + (size_t)(k32 * 32) * ldw + sc;
;     f32x4 v[32];
; #pragma unroll
;     for (int i = 0; i < 32; ++i) v[i] = __builtin_nontemporal_load((const f32x4*)(src + (size_t)i * ldw));
;     if (gk) {
; #pragma unroll
;         for (int i = 0; i < 32; ++i) v[i] *= gk[k32 * 32 + i]; }
.LBB0_847:
	s_add_i32 s6, s12, s1
	s_cmp_ge_u32 s6, s0
	s_cbranch_scc1 .LBB0_846
	s_mul_hi_i32 s6, s1, 0x2e8ba2e9
	s_lshr_b32 s7, s6, 31
	s_ashr_i32 s41, s6, 3
	s_add_i32 s41, s41, s7
	s_mul_i32 s6, s41, 0xffffd400
	s_add_i32 s42, s40, s6
	s_mul_i32 s6, s41, 0xffffea00
	s_lshl_b32 s28, s41, 5
	v_add_u32_e32 v0, s6, v138
	s_ashr_i32 s29, s28, 31
	s_mul_i32 s6, s41, 0x160000
	s_mul_hi_i32 s7, s28, 0xb000
	s_add_u32 s6, s13, s6
	s_addc_u32 s7, s38, s7
	v_ashrrev_i32_e32 v1, 31, v0
	v_lshl_add_u64 v[4:5], v[0:1], 2, s[6:7]
	v_add_co_u32_e32 v0, vcc, s56, v4
	s_mov_b32 s6, 0x16000
	s_nop 0
	v_addc_co_u32_e32 v1, vcc, 0, v5, vcc
	global_load_dwordx4 v[64:67], v[4:5], off nt
	global_load_dwordx4 v[68:71], v[0:1], off nt
	v_add_co_u32_e32 v0, vcc, s6, v4
	s_mov_b32 s6, 0x21000
	s_nop 0
	v_addc_co_u32_e32 v1, vcc, 0, v5, vcc
	global_load_dwordx4 v[72:75], v[0:1], off nt
	v_add_co_u32_e32 v0, vcc, s6, v4
	s_mov_b32 s6, 0x2c000
	s_nop 0
	v_addc_co_u32_e32 v1, vcc, 0, v5, vcc
	global_load_dwordx4 v[76:79], v[0:1], off nt
	v_add_co_u32_e32 v0, vcc, s6, v4
	s_mov_b32 s6, 0x37000
	s_nop 0
	v_addc_co_u32_e32 v1, vcc, 0, v5, vcc
	global_load_dwordx4 v[80:83], v[0:1], off nt
	v_add_co_u32_e32 v0, vcc, s6, v4
	s_mov_b32 s6, 0x42000
	s_nop 0
	v_addc_co_u32_e32 v1, vcc, 0, v5, vcc
	global_load_dwordx4 v[84:87], v[0:1], off nt
	v_add_co_u32_e32 v0, vcc, s6, v4
	s_mov_b32 s6, 0x4d000
	s_nop 0
	v_addc_co_u32_e32 v1, vcc, 0, v5, vcc
	global_load_dwordx4 v[88:91], v[0:1], off nt
	v_add_co_u32_e32 v0, vcc, s6, v4
	s_mov_b32 s6, 0x58000
	s_nop 0
	v_addc_co_u32_e32 v1, vcc, 0, v5, vcc
	global_load_dwordx4 v[92:95], v[0:1], off nt
	v_add_co_u32_e32 v0, vcc, s6, v4
	s_mov_b32 s6, 0x63000
	s_nop 0
	v_addc_co_u32_e32 v1, vcc, 0, v5, vcc
	global_load_dwordx4 v[96:99], v[0:1], off nt
	v_add_co_u32_e32 v0, vcc, s6, v4
	s_mov_b32 s6, 0x6e000
	s_nop 0
	v_addc_co_u32_e32 v1, vcc, 0, v5, vcc
	global_load_dwordx4 v[100:103], v[0:1], off nt
	v_add_co_u32_e32 v0, vcc, s6, v4
	s_mov_b32 s6, 0x79000
	s_nop 0
	v_addc_co_u32_e32 v1, vcc, 0, v5, vcc
	global_load_dwordx4 v[104:107], v[0:1], off nt
	v_add_co_u32_e32 v0, vcc, s6, v4
	s_mov_b32 s6, 0x84000
	s_nop 0
	v_addc_co_u32_e32 v1, vcc, 0, v5, vcc
	global_load_dwordx4 v[108:111], v[0:1], off nt
	v_add_co_u32_e32 v0, vcc, s6, v4
	s_mov_b32 s6, 0x8f000
	s_nop 0
	v_addc_co_u32_e32 v1, vcc, 0, v5, vcc
	global_load_dwordx4 v[112:115], v[0:1], off nt
	v_add_co_u32_e32 v0, vcc, s6, v4
	s_mov_b32 s6, 0x9a000
	s_nop 0
	v_addc_co_u32_e32 v1, vcc, 0, v5, vcc
	global_load_dwordx4 v[116:119], v[0:1], off nt
	v_add_co_u32_e32 v0, vcc, s6, v4
	s_mov_b32 s6, 0xa5000
	s_nop 0
	v_addc_co_u32_e32 v1, vcc, 0, v5, vcc
	global_load_dwordx4 v[120:123], v[0:1], off nt
	v_add_co_u32_e32 v0, vcc, s6, v4
	s_mov_b32 s6, 0xb0000
	s_nop 0
	v_addc_co_u32_e32 v1, vcc, 0, v5, vcc
	global_load_dwordx4 v[124:127], v[0:1], off nt
	v_add_co_u32_e32 v0, vcc, s6, v4
	s_mov_b32 s6, 0xbb000
	s_nop 0
	v_addc_co_u32_e32 v1, vcc, 0, v5, vcc
	v_add_co_u32_e32 v6, vcc, s6, v4
	s_mov_b32 s6, 0xc6000
	s_nop 0
	v_addc_co_u32_e32 v7, vcc, 0, v5, vcc
	global_load_dwordx4 v[60:63], v[6:7], off nt
	v_add_co_u32_e32 v6, vcc, s6, v4
	s_mov_b32 s6, 0xd1000
	s_nop 0
	v_addc_co_u32_e32 v7, vcc, 0, v5, vcc
	global_load_dwordx4 v[56:59], v[6:7], off nt
	v_add_co_u32_e32 v6, vcc, s6, v4
	s_mov_b32 s6, 0xdc000
	s_nop 0
	v_addc_co_u32_e32 v7, vcc, 0, v5, vcc
	global_load_dwordx4 v[44:47], v[6:7], off nt
	v_add_co_u32_e32 v6, vcc, s6, v4
	s_mov_b32 s6, 0xe7000
	s_nop 0
	v_addc_co_u32_e32 v7, vcc, 0, v5, vcc
	global_load_dwordx4 v[48:51], v[6:7], off nt
	v_add_co_u32_e32 v6, vcc, s6, v4
	s_mov_b32 s6, 0xf2000
	s_nop 0
	v_addc_co_u32_e32 v7, vcc, 0, v5, vcc
	global_load_dwordx4 v[52:55], v[6:7], off nt
	v_add_co_u32_e32 v6, vcc, s6, v4
	s_mov_b32 s6, 0xfd000
	s_nop 0
	v_addc_co_u32_e32 v7, vcc, 0, v5, vcc
	global_load_dwordx4 v[40:43], v[6:7], off nt
	v_add_co_u32_e32 v6, vcc, s6, v4
	s_mov_b32 s6, 0x108000
	s_nop 0
	v_addc_co_u32_e32 v7, vcc, 0, v5, vcc
	global_load_dwordx4 v[28:31], v[6:7], off nt
	v_add_co_u32_e32 v6, vcc, s6, v4
	s_mov_b32 s6, 0x113000
	s_nop 0
	v_addc_co_u32_e32 v7, vcc, 0, v5, vcc
	global_load_dwordx4 v[32:35], v[6:7], off nt
	v_add_co_u32_e32 v6, vcc, s6, v4
	s_mov_b32 s6, 0x11e000
	s_nop 0
	v_addc_co_u32_e32 v7, vcc, 0, v5, vcc
	global_load_dwordx4 v[36:39], v[6:7], off nt
	v_add_co_u32_e32 v6, vcc, s6, v4
	s_mov_b32 s6, 0x129000
	s_nop 0
	v_addc_co_u32_e32 v7, vcc, 0, v5, vcc
	global_load_dwordx4 v[24:27], v[6:7], off nt
	v_add_co_u32_e32 v6, vcc, s6, v4
	s_mov_b32 s6, 0x134000
	s_nop 0
	v_addc_co_u32_e32 v7, vcc, 0, v5, vcc
	global_load_dwordx4 v[12:15], v[6:7], off nt
	v_add_co_u32_e32 v6, vcc, s6, v4
	s_mov_b32 s6, 0x13f000
	s_nop 0
	v_addc_co_u32_e32 v7, vcc, 0, v5, vcc
	global_load_dwordx4 v[16:19], v[6:7], off nt
	v_add_co_u32_e32 v6, vcc, s6, v4
	s_mov_b32 s6, 0x14a000
	s_nop 0
	v_addc_co_u32_e32 v7, vcc, 0, v5, vcc
	global_load_dwordx4 v[20:23], v[6:7], off nt
	v_add_co_u32_e32 v6, vcc, s6, v4
	s_mov_b32 s6, 0x155000
	s_nop 0
	v_addc_co_u32_e32 v7, vcc, 0, v5, vcc
	v_add_co_u32_e32 v4, vcc, s6, v4
	s_lshl_b64 s[6:7], s[28:29], 2
	s_add_u32 s28, s30, s6
	v_addc_co_u32_e32 v5, vcc, 0, v5, vcc
	s_addc_u32 s29, s39, s7
	global_load_dwordx4 v[0:3], v[0:1], off nt
	s_mul_hi_i32 s7, s41, 0x2c00
	global_load_dwordx4 v[8:11], v[6:7], off nt
	s_mulk_i32 s41, 0x2c00
	global_load_dwordx4 v[4:7], v[4:5], off nt
	s_nop 0
	global_load_dwordx4 v[164:167], v139, s[28:29] offset:48
	global_load_dwordx4 v[168:171], v139, s[28:29] offset:32
	global_load_dwordx4 v[154:157], v139, s[28:29] offset:16
	global_load_dwordx4 v[146:149], v139, s[28:29]
	s_waitcnt vmcnt(1)
; __device__ __forceinline__ void conv_item(const float* W, int ldw, int Nout, int mode, const float* gk, unsigned char* dst, int item, int lane, LAS unsigned char* wl  ) {
;     ...
;     if (gk) {
; #pragma unroll
;         for (int i = 0; i < 32; ++i) v[i] *= gk[k32 * 32 + i]; }
	v_pk_mul_f32 v[82:83], v[82:83], v[154:155] op_sel_hi:[1,0]
	s_waitcnt vmcnt(0)
	v_pk_mul_f32 v[142:143], v[64:65], v[146:147] op_sel_hi:[1,0]
	v_mov_b32_e32 v64, v149
	v_pk_mul_f32 v[136:137], v[78:79], v[64:65] op_sel_hi:[1,0]
	v_pk_mul_f32 v[150:151], v[76:77], v[64:65] op_sel_hi:[1,0]
	v_mov_b32_e32 v64, v157
	v_pk_mul_f32 v[132:133], v[74:75], v[148:149] op_sel_hi:[1,0]
	v_pk_mul_f32 v[144:145], v[72:73], v[148:149] op_sel_hi:[1,0]
	v_pk_mul_f32 v[148:149], v[80:81], v[154:155] op_sel_hi:[1,0]
	v_pk_mul_f32 v[140:141], v[86:87], v[154:155] op_sel:[0,1]
	v_pk_mul_f32 v[154:155], v[84:85], v[154:155] op_sel:[0,1]
	v_pk_mul_f32 v[84:85], v[90:91], v[156:157] op_sel_hi:[1,0]
	v_pk_mul_f32 v[152:153], v[88:89], v[156:157] op_sel_hi:[1,0]
	v_pk_mul_f32 v[94:95], v[94:95], v[64:65] op_sel_hi:[1,0]
	v_pk_mul_f32 v[156:157], v[92:93], v[64:65] op_sel_hi:[1,0]
	v_mov_b32_e32 v64, v171
	v_pk_mul_f32 v[78:79], v[106:107], v[170:171] op_sel_hi:[1,0]
	v_pk_mul_f32 v[88:89], v[110:111], v[64:65] op_sel_hi:[1,0]
	v_pk_mul_f32 v[106:107], v[108:109], v[64:65] op_sel_hi:[1,0]
	v_mov_b32_e32 v64, v167
	v_pk_mul_f32 v[130:131], v[66:67], v[146:147] op_sel_hi:[1,0]
	v_pk_mul_f32 v[134:135], v[70:71], v[146:147] op_sel:[0,1]
	v_pk_mul_f32 v[146:147], v[68:69], v[146:147] op_sel:[0,1]
	v_pk_mul_f32 v[76:77], v[98:99], v[168:169] op_sel_hi:[1,0]
	v_pk_mul_f32 v[98:99], v[96:97], v[168:169] op_sel_hi:[1,0]
	v_pk_mul_f32 v[80:81], v[102:103], v[168:169] op_sel:[0,1]
	v_pk_mul_f32 v[102:103], v[100:101], v[168:169] op_sel:[0,1]
	v_pk_mul_f32 v[100:101], v[104:105], v[170:171] op_sel_hi:[1,0]
	v_pk_mul_f32 v[86:87], v[114:115], v[164:165] op_sel_hi:[1,0]
	v_pk_mul_f32 v[104:105], v[112:113], v[164:165] op_sel_hi:[1,0]
	v_pk_mul_f32 v[110:111], v[116:117], v[164:165] op_sel:[0,1]
	v_pk_mul_f32 v[96:97], v[126:127], v[64:65] op_sel_hi:[1,0]
	v_pk_mul_f32 v[112:113], v[124:125], v[64:65] op_sel_hi:[1,0]
	global_load_dwordx4 v[64:67], v139, s[28:29] offset:112
	global_load_dwordx4 v[68:71], v139, s[28:29] offset:96
	global_load_dwordx4 v[72:75], v139, s[28:29] offset:80
	global_load_dwordx4 v[114:117], v139, s[28:29] offset:64
	v_pk_mul_f32 v[92:93], v[118:119], v[164:165] op_sel:[0,1]
	v_pk_mul_f32 v[108:109], v[120:121], v[166:167] op_sel_hi:[1,0]
	v_pk_mul_f32 v[90:91], v[122:123], v[166:167] op_sel_hi:[1,0]
	s_ashr_i32 s28, s42, 31
	s_add_u32 s6, s41, s42
	s_addc_u32 s7, s7, s28
	s_lshl_b64 s[6:7], s[6:7], 6
	s_waitcnt vmcnt(3)
	v_pk_mul_f32 v[8:9], v[8:9], v[66:67] op_sel_hi:[1,0]
	s_waitcnt vmcnt(2)
	v_pk_mul_f32 v[36:37], v[36:37], v[68:69] op_sel:[0,1]
	s_waitcnt vmcnt(1)
	v_pk_mul_f32 v[52:53], v[52:53], v[72:73] op_sel:[0,1]
	s_waitcnt vmcnt(0)
; #define LAS __attribute__((address_space(3)))
; __device__ __forceinline__ unsigned cvt_pk_bf16(float lo, float hi) { unsigned r; asm volatile("v_cvt_pk_bf16_f32 %0, %1, %2" : "=v"(r) : "v"(lo), "v"(hi)); return r; }
; __device__ __forceinline__ void conv_item(const float* W, int ldw, int Nout, int mode, const float* gk, unsigned char* dst, int item, int lane, LAS unsigned char* wl  ) {
;     ...
;     LAS unsigned char* mine = wl + lane * 272;
; #pragma unroll
;     for (int j = 0; j < 4; ++j)
; #pragma unroll
;         for (int q = 0; q < 4; ++q) { u32x4 w;
;             w.x = cvt_pk_bf16(v[8 * q + 0][j], v[8 * q + 1][j]); w.y = cvt_pk_bf16(v[8 * q + 2][j], v[8 * q + 3][j]);
;             w.z = cvt_pk_bf16(v[8 * q + 4][j], v[8 * q + 5][j]); w.w = cvt_pk_bf16(v[8 * q + 6][j], v[8 * q + 7][j]);
;             *(LAS u32x4*)(mine + (j * 4 + q) * 16) = w; }
;     asm volatile("s_waitcnt lgkmcnt(0)" ::: "memory");
;     unsigned char* d = dst + ((size_t)k32 * Nout + nb0) * 64 + lane * 16;
;     const LAS unsigned char* rd = wl + (lane >> 4) * 272 + (lane & 15) * 16;
; #pragma unroll
;     for (int s = 0; s < 16; ++s) { const u32x4 w = *(const LAS u32x4*)(rd + s * 4 * 272); *(u32x4*)(d + s * 1024) = w; }
;     asm volatile("s_waitcnt lgkmcnt(0)" ::: "memory");
	v_pk_mul_f32 v[118:119], v[0:1], v[114:115] op_sel_hi:[1,0]
	v_pk_mul_f32 v[0:1], v[62:63], v[114:115] op_sel:[0,1]
	v_mov_b32_e32 v62, v117
	v_pk_mul_f32 v[46:47], v[46:47], v[62:63] op_sel_hi:[1,0]
	v_pk_mul_f32 v[62:63], v[44:45], v[62:63] op_sel_hi:[1,0]
	v_pk_mul_f32 v[44:45], v[50:51], v[72:73] op_sel_hi:[1,0]
	v_pk_mul_f32 v[50:51], v[48:49], v[72:73] op_sel_hi:[1,0]
	v_pk_mul_f32 v[48:49], v[54:55], v[72:73] op_sel:[0,1]
	v_mov_b32_e32 v54, v75
	v_pk_mul_f32 v[30:31], v[30:31], v[54:55] op_sel_hi:[1,0]
	v_pk_mul_f32 v[54:55], v[28:29], v[54:55] op_sel_hi:[1,0]
	v_pk_mul_f32 v[28:29], v[34:35], v[68:69] op_sel_hi:[1,0]
	v_pk_mul_f32 v[34:35], v[32:33], v[68:69] op_sel_hi:[1,0]
	v_pk_mul_f32 v[32:33], v[38:39], v[68:69] op_sel:[0,1]
	v_mov_b32_e32 v38, v71
	v_pk_mul_f32 v[14:15], v[14:15], v[38:39] op_sel_hi:[1,0]
	v_pk_mul_f32 v[38:39], v[12:13], v[38:39] op_sel_hi:[1,0]
	v_pk_mul_f32 v[12:13], v[18:19], v[64:65] op_sel_hi:[1,0]
	v_mov_b32_e32 v18, v67
	v_pk_mul_f32 v[68:69], v[16:17], v[64:65] op_sel_hi:[1,0]
	v_pk_mul_f32 v[16:17], v[22:23], v[64:65] op_sel:[0,1]
	v_pk_mul_f32 v[22:23], v[20:21], v[64:65] op_sel:[0,1]
	v_pk_mul_f32 v[6:7], v[6:7], v[18:19] op_sel_hi:[1,0]
	v_pk_mul_f32 v[4:5], v[4:5], v[18:19] op_sel_hi:[1,0]
	v_cvt_pk_bf16_f32 v18, v142, v146
	v_cvt_pk_bf16_f32 v19, v144, v150
	v_cvt_pk_bf16_f32 v20, v148, v154
	v_cvt_pk_bf16_f32 v21, v152, v156
	ds_write_b128 v158, v[18:21]
	v_cvt_pk_bf16_f32 v18, v98, v102
	v_cvt_pk_bf16_f32 v19, v100, v106
	v_cvt_pk_bf16_f32 v20, v104, v110
	v_cvt_pk_bf16_f32 v21, v108, v112
	v_pk_mul_f32 v[60:61], v[60:61], v[114:115] op_sel:[0,1]
	v_pk_mul_f32 v[56:57], v[56:57], v[116:117] op_sel_hi:[1,0]
	v_pk_mul_f32 v[40:41], v[40:41], v[74:75] op_sel_hi:[1,0]
	ds_write_b128 v158, v[18:21] offset:16
	v_cvt_pk_bf16_f32 v18, v118, v60
	v_cvt_pk_bf16_f32 v19, v56, v62
	v_cvt_pk_bf16_f32 v20, v50, v52
	v_cvt_pk_bf16_f32 v21, v40, v54
	v_pk_mul_f32 v[24:25], v[24:25], v[70:71] op_sel_hi:[1,0]
	ds_write_b128 v158, v[18:21] offset:32
	v_cvt_pk_bf16_f32 v18, v34, v36
	v_cvt_pk_bf16_f32 v19, v24, v38
	v_cvt_pk_bf16_f32 v20, v68, v22
	v_cvt_pk_bf16_f32 v21, v8, v4
	ds_write_b128 v158, v[18:21] offset:48
	v_cvt_pk_bf16_f32 v18, v143, v147
	v_cvt_pk_bf16_f32 v19, v145, v151
	v_cvt_pk_bf16_f32 v20, v149, v155
	v_cvt_pk_bf16_f32 v21, v153, v157
	ds_write_b128 v158, v[18:21] offset:64
	v_cvt_pk_bf16_f32 v18, v99, v103
	v_cvt_pk_bf16_f32 v19, v101, v107
	v_cvt_pk_bf16_f32 v20, v105, v111
	v_cvt_pk_bf16_f32 v21, v109, v113
	ds_write_b128 v158, v[18:21] offset:80
	v_cvt_pk_bf16_f32 v18, v119, v61
	v_cvt_pk_bf16_f32 v19, v57, v63
	v_cvt_pk_bf16_f32 v20, v51, v53
	v_cvt_pk_bf16_f32 v21, v41, v55
	ds_write_b128 v158, v[18:21] offset:96
	v_cvt_pk_bf16_f32 v18, v35, v37
	v_cvt_pk_bf16_f32 v19, v25, v39
	v_cvt_pk_bf16_f32 v20, v69, v23
	v_cvt_pk_bf16_f32 v21, v9, v5
	ds_write_b128 v158, v[18:21] offset:112
	v_cvt_pk_bf16_f32 v18, v130, v134
	v_cvt_pk_bf16_f32 v19, v132, v136
	v_cvt_pk_bf16_f32 v20, v82, v140
	v_cvt_pk_bf16_f32 v21, v84, v94
	ds_write_b128 v158, v[18:21] offset:128
	v_cvt_pk_bf16_f32 v18, v76, v80
	v_cvt_pk_bf16_f32 v19, v78, v88
	v_cvt_pk_bf16_f32 v20, v86, v92
	v_cvt_pk_bf16_f32 v21, v90, v96
	v_pk_mul_f32 v[2:3], v[2:3], v[114:115] op_sel_hi:[1,0]
	v_pk_mul_f32 v[58:59], v[58:59], v[116:117] op_sel_hi:[1,0]
	v_pk_mul_f32 v[42:43], v[42:43], v[74:75] op_sel_hi:[1,0]
	ds_write_b128 v158, v[18:21] offset:144
	v_cvt_pk_bf16_f32 v18, v2, v0
	v_cvt_pk_bf16_f32 v19, v58, v46
	v_cvt_pk_bf16_f32 v20, v44, v48
	v_cvt_pk_bf16_f32 v21, v42, v30
	v_pk_mul_f32 v[26:27], v[26:27], v[70:71] op_sel_hi:[1,0]
	v_pk_mul_f32 v[10:11], v[10:11], v[66:67] op_sel_hi:[1,0]
	ds_write_b128 v158, v[18:21] offset:160
	v_cvt_pk_bf16_f32 v18, v28, v32
	v_cvt_pk_bf16_f32 v19, v26, v14
	v_cvt_pk_bf16_f32 v20, v12, v16
	v_cvt_pk_bf16_f32 v21, v10, v6
	ds_write_b128 v158, v[18:21] offset:176
	v_cvt_pk_bf16_f32 v18, v131, v135
	v_cvt_pk_bf16_f32 v19, v133, v137
	v_cvt_pk_bf16_f32 v20, v83, v141
	v_cvt_pk_bf16_f32 v21, v85, v95
	ds_write_b128 v158, v[18:21] offset:192
	v_cvt_pk_bf16_f32 v18, v77, v81
	v_cvt_pk_bf16_f32 v19, v79, v89
	v_cvt_pk_bf16_f32 v20, v87, v93
	v_cvt_pk_bf16_f32 v21, v91, v97
	ds_write_b128 v158, v[18:21] offset:208
	v_cvt_pk_bf16_f32 v0, v3, v1
	v_cvt_pk_bf16_f32 v1, v59, v47
	v_cvt_pk_bf16_f32 v2, v45, v49
	v_cvt_pk_bf16_f32 v3, v43, v31
	ds_write_b128 v158, v[0:3] offset:224
	v_cvt_pk_bf16_f32 v0, v29, v33
	v_cvt_pk_bf16_f32 v1, v27, v15
	v_cvt_pk_bf16_f32 v2, v13, v17
	v_cvt_pk_bf16_f32 v3, v11, v7
	ds_write_b128 v158, v[0:3] offset:240
	s_waitcnt lgkmcnt(0)
	ds_read_b128 v[0:3], v159
	v_lshl_add_u64 v[4:5], v[128:129], 0, s[6:7]
	v_add_co_u32_e32 v6, vcc, s34, v4
	s_waitcnt lgkmcnt(0)
	global_store_dwordx4 v[4:5], v[0:3], off nt
	ds_read_b128 v[0:3], v159 offset:1088
	v_addc_co_u32_e32 v7, vcc, 0, v5, vcc
	v_add_co_u32_e32 v8, vcc, s60, v4
	s_waitcnt lgkmcnt(0)
	global_store_dwordx4 v[4:5], v[0:3], off offset:1024 nt
	ds_read_b128 v[0:3], v159 offset:2176
	v_addc_co_u32_e32 v9, vcc, 0, v5, vcc
	s_waitcnt lgkmcnt(0)
	global_store_dwordx4 v[4:5], v[0:3], off offset:2048 nt
	ds_read_b128 v[0:3], v159 offset:3264
	s_waitcnt lgkmcnt(0)
	global_store_dwordx4 v[4:5], v[0:3], off offset:3072 nt
	ds_read_b128 v[0:3], v159 offset:4352
	v_add_co_u32_e32 v4, vcc, 0x3000, v4
	s_waitcnt lgkmcnt(0)
	global_store_dwordx4 v[8:9], v[0:3], off offset:-4096 nt
	ds_read_b128 v[0:3], v159 offset:5440
	v_addc_co_u32_e32 v5, vcc, 0, v5, vcc
	s_waitcnt lgkmcnt(0)
	global_store_dwordx4 v[6:7], v[0:3], off offset:1024 nt
	ds_read_b128 v[0:3], v159 offset:6528
	s_waitcnt lgkmcnt(0)
	global_store_dwordx4 v[6:7], v[0:3], off offset:2048 nt
	ds_read_b128 v[0:3], v159 offset:7616
	s_waitcnt lgkmcnt(0)
	global_store_dwordx4 v[6:7], v[0:3], off offset:3072 nt
	ds_read_b128 v[0:3], v159 offset:8704
	s_waitcnt lgkmcnt(0)
	global_store_dwordx4 v[8:9], v[0:3], off nt
	ds_read_b128 v[0:3], v159 offset:9792
	s_waitcnt lgkmcnt(0)
	global_store_dwordx4 v[8:9], v[0:3], off offset:1024 nt
	ds_read_b128 v[0:3], v159 offset:10880
	s_waitcnt lgkmcnt(0)
	global_store_dwordx4 v[8:9], v[0:3], off offset:2048 nt
	ds_read_b128 v[0:3], v159 offset:11968
	s_waitcnt lgkmcnt(0)
	global_store_dwordx4 v[8:9], v[0:3], off offset:3072 nt
	ds_read_b128 v[0:3], v159 offset:13056
	s_waitcnt lgkmcnt(0)
	global_store_dwordx4 v[4:5], v[0:3], off nt
	ds_read_b128 v[0:3], v159 offset:14144
	s_waitcnt lgkmcnt(0)
	global_store_dwordx4 v[4:5], v[0:3], off offset:1024 nt
	ds_read_b128 v[0:3], v159 offset:15232
	s_waitcnt lgkmcnt(0)
	global_store_dwordx4 v[4:5], v[0:3], off offset:2048 nt
	ds_read_b128 v[0:3], v159 offset:16320
	s_waitcnt lgkmcnt(0)
	global_store_dwordx4 v[4:5], v[0:3], off offset:3072 nt
	s_waitcnt lgkmcnt(0)
	s_branch .LBB0_846

; __device__ __forceinline__ void conv_item(const float* W, int ldw, int Nout, int mode, const float* gk, unsigned char* dst, int item, int lane, LAS unsigned char* wl  ) {
;     const int nblk = Nout >> 8, k32 = item / nblk, nb0 = (item - k32 * nblk) * 256, nb = nb0 + lane * 4;
;     int sc = nb; if (mode == 1) sc = ((nb >> 7) & 1) * FF + (nb >> 8) * 128 + (nb & 127);
;     const float* src = W + (size_t)(k32 * 32) * ldw + sc;
;     f32x4 v[32];
; #pragma unroll
;     for (int i = 0; i < 32; ++i) v[i] = __builtin_nontemporal_load((const f32x4*)(src + (size_t)i * ldw));
;     if (gk) {
; #pragma unroll
;         for (int i = 0; i < 32; ++i) v[i] *= gk[k32 * 32 + i]; }
.LBB0_853:
	s_cmpk_lt_i32 s0, 0x754
	s_cbranch_scc1 .LBB0_852
	s_and_b32 s6, s0, 0xffff
	s_mul_hi_u32 s7, s6, 0x5d1745e
	s_mul_i32 s6, s6, 0xba2f
	s_mul_i32 s12, s7, 0x1600
	s_mulk_i32 s7, 0x2c00
	s_lshr_b32 s13, s6, 21
	v_subrev_u32_e32 v0, s12, v138
	s_sub_i32 s12, s1, s7
	s_mul_i32 s6, s13, 0x160000
	s_add_u32 s6, s28, s6
	v_readlane_b32 s7, v255, 5
	s_addc_u32 s7, s7, 0
	v_ashrrev_i32_e32 v1, 31, v0
	v_lshl_add_u64 v[60:61], v[0:1], 2, s[6:7]
	v_add_co_u32_e32 v0, vcc, s29, v60
	s_mov_b32 s6, 0x16000
	s_nop 0
	v_addc_co_u32_e32 v1, vcc, 0, v61, vcc
	global_load_dwordx4 v[64:67], v[60:61], off nt
	global_load_dwordx4 v[68:71], v[0:1], off nt
	v_add_co_u32_e32 v0, vcc, s6, v60
	s_mov_b32 s6, 0x21000
	s_nop 0
	v_addc_co_u32_e32 v1, vcc, 0, v61, vcc
	global_load_dwordx4 v[72:75], v[0:1], off nt
	v_add_co_u32_e32 v0, vcc, s6, v60
	s_mov_b32 s6, 0x2c000
	s_nop 0
	v_addc_co_u32_e32 v1, vcc, 0, v61, vcc
	global_load_dwordx4 v[76:79], v[0:1], off nt
	v_add_co_u32_e32 v0, vcc, s6, v60
	s_mov_b32 s6, 0x37000
	s_nop 0
	v_addc_co_u32_e32 v1, vcc, 0, v61, vcc
	global_load_dwordx4 v[80:83], v[0:1], off nt
	v_add_co_u32_e32 v0, vcc, s6, v60
	s_mov_b32 s6, 0x42000
	s_nop 0
	v_addc_co_u32_e32 v1, vcc, 0, v61, vcc
	global_load_dwordx4 v[84:87], v[0:1], off nt
	v_add_co_u32_e32 v0, vcc, s6, v60
	s_mov_b32 s6, 0x4d000
	s_nop 0
	v_addc_co_u32_e32 v1, vcc, 0, v61, vcc
	global_load_dwordx4 v[88:91], v[0:1], off nt
	v_add_co_u32_e32 v0, vcc, s6, v60
	s_mov_b32 s6, 0x58000
	s_nop 0
	v_addc_co_u32_e32 v1, vcc, 0, v61, vcc
	global_load_dwordx4 v[92:95], v[0:1], off nt
	v_add_co_u32_e32 v0, vcc, s6, v60
	s_mov_b32 s6, 0x63000
	s_nop 0
	v_addc_co_u32_e32 v1, vcc, 0, v61, vcc
	global_load_dwordx4 v[96:99], v[0:1], off nt
	v_add_co_u32_e32 v0, vcc, s6, v60
	s_mov_b32 s6, 0x6e000
	s_nop 0
	v_addc_co_u32_e32 v1, vcc, 0, v61, vcc
	global_load_dwordx4 v[100:103], v[0:1], off nt
	v_add_co_u32_e32 v0, vcc, s6, v60
	s_mov_b32 s6, 0x79000
	s_nop 0
	v_addc_co_u32_e32 v1, vcc, 0, v61, vcc
	global_load_dwordx4 v[104:107], v[0:1], off nt
	v_add_co_u32_e32 v0, vcc, s6, v60
	s_mov_b32 s6, 0x84000
	s_nop 0
	v_addc_co_u32_e32 v1, vcc, 0, v61, vcc
	global_load_dwordx4 v[108:111], v[0:1], off nt
	v_add_co_u32_e32 v0, vcc, s6, v60
	s_mov_b32 s6, 0x8f000
	s_nop 0
	v_addc_co_u32_e32 v1, vcc, 0, v61, vcc
	global_load_dwordx4 v[112:115], v[0:1], off nt
	v_add_co_u32_e32 v0, vcc, s6, v60
	s_mov_b32 s6, 0x9a000
	s_nop 0
	v_addc_co_u32_e32 v1, vcc, 0, v61, vcc
	global_load_dwordx4 v[116:119], v[0:1], off nt
	v_add_co_u32_e32 v0, vcc, s6, v60
	s_mov_b32 s6, 0xa5000
	s_nop 0
	v_addc_co_u32_e32 v1, vcc, 0, v61, vcc
	global_load_dwordx4 v[120:123], v[0:1], off nt
	v_add_co_u32_e32 v0, vcc, s6, v60
	s_mov_b32 s6, 0xb0000
	s_nop 0
	v_addc_co_u32_e32 v1, vcc, 0, v61, vcc
	global_load_dwordx4 v[124:127], v[0:1], off nt
	v_add_co_u32_e32 v0, vcc, s6, v60
	s_mov_b32 s6, 0xbb000
	s_nop 0
	v_addc_co_u32_e32 v1, vcc, 0, v61, vcc
	v_add_co_u32_e32 v4, vcc, s6, v60
	s_mov_b32 s6, 0xc6000
	s_nop 0
	v_addc_co_u32_e32 v5, vcc, 0, v61, vcc
	v_add_co_u32_e32 v8, vcc, s6, v60
	s_mov_b32 s6, 0xd1000
	s_nop 0
	v_addc_co_u32_e32 v9, vcc, 0, v61, vcc
	v_add_co_u32_e32 v12, vcc, s6, v60
	s_mov_b32 s6, 0xdc000
	s_nop 0
	v_addc_co_u32_e32 v13, vcc, 0, v61, vcc
	v_add_co_u32_e32 v16, vcc, s6, v60
	s_mov_b32 s6, 0xe7000
	s_nop 0
	v_addc_co_u32_e32 v17, vcc, 0, v61, vcc
	v_add_co_u32_e32 v20, vcc, s6, v60
	s_mov_b32 s6, 0xf2000
	s_nop 0
	v_addc_co_u32_e32 v21, vcc, 0, v61, vcc
	v_add_co_u32_e32 v24, vcc, s6, v60
	s_mov_b32 s6, 0xfd000
	s_nop 0
	v_addc_co_u32_e32 v25, vcc, 0, v61, vcc
	v_add_co_u32_e32 v28, vcc, s6, v60
	s_mov_b32 s6, 0x108000
	s_nop 0
	v_addc_co_u32_e32 v29, vcc, 0, v61, vcc
	v_add_co_u32_e32 v32, vcc, s6, v60
	s_mov_b32 s6, 0x113000
	s_nop 0
	v_addc_co_u32_e32 v33, vcc, 0, v61, vcc
	v_add_co_u32_e32 v36, vcc, s6, v60
	s_mov_b32 s6, 0x11e000
	s_nop 0
	v_addc_co_u32_e32 v37, vcc, 0, v61, vcc
	v_add_co_u32_e32 v40, vcc, s6, v60
	s_mov_b32 s6, 0x129000
	s_nop 0
	v_addc_co_u32_e32 v41, vcc, 0, v61, vcc
	v_add_co_u32_e32 v44, vcc, s6, v60
	s_mov_b32 s6, 0x134000
	s_nop 0
	v_addc_co_u32_e32 v45, vcc, 0, v61, vcc
	v_add_co_u32_e32 v48, vcc, s6, v60
	s_mov_b32 s6, 0x13f000
	s_nop 0
	v_addc_co_u32_e32 v49, vcc, 0, v61, vcc
	v_add_co_u32_e32 v52, vcc, s6, v60
	s_mov_b32 s6, 0x14a000
	s_nop 0
	v_addc_co_u32_e32 v53, vcc, 0, v61, vcc
	v_add_co_u32_e32 v56, vcc, s6, v60
	s_mov_b32 s6, 0x155000
	s_nop 0
	v_addc_co_u32_e32 v57, vcc, 0, v61, vcc
	v_add_co_u32_e32 v60, vcc, s6, v60
	s_lshl_b32 s6, s13, 7
	v_mov_b32_e32 v165, s6
	v_readlane_b32 s6, v255, 6
	v_addc_co_u32_e32 v61, vcc, 0, v61, vcc
	v_readlane_b32 s7, v255, 7
	global_load_dwordx4 v[0:3], v[0:1], off nt
	s_mulk_i32 s13, 0x2c00
	global_load_dwordx4 v[4:7], v[4:5], off nt
	s_nop 0
	global_load_dwordx4 v[8:11], v[8:9], off nt
	s_nop 0
	global_load_dwordx4 v[12:15], v[12:13], off nt
	s_nop 0
	global_load_dwordx4 v[16:19], v[16:17], off nt
	s_nop 0
	global_load_dwordx4 v[20:23], v[20:21], off nt
	s_nop 0
	global_load_dwordx4 v[24:27], v[24:25], off nt
	s_nop 0
	global_load_dwordx4 v[28:31], v[28:29], off nt
	s_nop 0
	global_load_dwordx4 v[32:35], v[32:33], off nt
	s_nop 0
	global_load_dwordx4 v[36:39], v[36:37], off nt
	s_nop 0
	global_load_dwordx4 v[40:43], v[40:41], off nt
	s_nop 0
	global_load_dwordx4 v[44:47], v[44:45], off nt
	s_nop 0
	global_load_dwordx4 v[48:51], v[48:49], off nt
	s_nop 0
	global_load_dwordx4 v[52:55], v[52:53], off nt
	s_nop 0
	global_load_dwordx4 v[56:59], v[56:57], off nt
	s_nop 0
	global_load_dwordx4 v[60:63], v[60:61], off nt
	s_nop 0
	global_load_dwordx4 v[166:169], v165, s[6:7] offset:48
	global_load_dwordx4 v[170:173], v165, s[6:7] offset:32
	global_load_dwordx4 v[158:161], v165, s[6:7] offset:16
	global_load_dwordx4 v[140:143], v165, s[6:7]
	s_waitcnt vmcnt(1)
; __device__ __forceinline__ void conv_item(const float* W, int ldw, int Nout, int mode, const float* gk, unsigned char* dst, int item, int lane, LAS unsigned char* wl  ) {
;     ...
;     if (gk) {
; #pragma unroll
;         for (int i = 0; i < 32; ++i) v[i] *= gk[k32 * 32 + i]; }
	v_pk_mul_f32 v[156:157], v[88:89], v[160:161] op_sel_hi:[1,0]
	s_waitcnt vmcnt(0)
	v_pk_mul_f32 v[146:147], v[64:65], v[140:141] op_sel_hi:[1,0]
	v_mov_b32_e32 v64, v143
	v_pk_mul_f32 v[130:131], v[66:67], v[140:141] op_sel_hi:[1,0]
	v_pk_mul_f32 v[134:135], v[70:71], v[140:141] op_sel:[0,1]
	v_pk_mul_f32 v[150:151], v[68:69], v[140:141] op_sel:[0,1]
	v_pk_mul_f32 v[140:141], v[78:79], v[64:65] op_sel_hi:[1,0]
	v_pk_mul_f32 v[154:155], v[76:77], v[64:65] op_sel_hi:[1,0]
	v_mov_b32_e32 v64, v161
	v_pk_mul_f32 v[132:133], v[74:75], v[142:143] op_sel_hi:[1,0]
	v_pk_mul_f32 v[148:149], v[72:73], v[142:143] op_sel_hi:[1,0]
	v_pk_mul_f32 v[142:143], v[86:87], v[158:159] op_sel:[0,1]
	v_pk_mul_f32 v[86:87], v[90:91], v[160:161] op_sel_hi:[1,0]
	v_pk_mul_f32 v[144:145], v[94:95], v[64:65] op_sel_hi:[1,0]
	v_pk_mul_f32 v[160:161], v[92:93], v[64:65] op_sel_hi:[1,0]
	v_mov_b32_e32 v64, v173
	v_pk_mul_f32 v[136:137], v[82:83], v[158:159] op_sel_hi:[1,0]
	v_pk_mul_f32 v[82:83], v[106:107], v[172:173] op_sel_hi:[1,0]
	v_pk_mul_f32 v[90:91], v[110:111], v[64:65] op_sel_hi:[1,0]
	v_pk_mul_f32 v[106:107], v[108:109], v[64:65] op_sel_hi:[1,0]
	v_mov_b32_e32 v64, v169
	v_pk_mul_f32 v[152:153], v[80:81], v[158:159] op_sel_hi:[1,0]
	v_pk_mul_f32 v[158:159], v[84:85], v[158:159] op_sel:[0,1]
	v_pk_mul_f32 v[80:81], v[98:99], v[170:171] op_sel_hi:[1,0]
	v_pk_mul_f32 v[98:99], v[96:97], v[170:171] op_sel_hi:[1,0]
	v_pk_mul_f32 v[84:85], v[102:103], v[170:171] op_sel:[0,1]
	v_pk_mul_f32 v[102:103], v[100:101], v[170:171] op_sel:[0,1]
	v_pk_mul_f32 v[100:101], v[104:105], v[172:173] op_sel_hi:[1,0]
	v_pk_mul_f32 v[104:105], v[112:113], v[166:167] op_sel_hi:[1,0]
	v_pk_mul_f32 v[96:97], v[126:127], v[64:65] op_sel_hi:[1,0]
	v_pk_mul_f32 v[112:113], v[124:125], v[64:65] op_sel_hi:[1,0]
	global_load_dwordx4 v[64:67], v165, s[6:7] offset:112
	global_load_dwordx4 v[68:71], v165, s[6:7] offset:96
	global_load_dwordx4 v[72:75], v165, s[6:7] offset:80
	global_load_dwordx4 v[76:79], v165, s[6:7] offset:64
	v_pk_mul_f32 v[110:111], v[116:117], v[166:167] op_sel:[0,1]
	v_pk_mul_f32 v[88:89], v[114:115], v[166:167] op_sel_hi:[1,0]
	v_pk_mul_f32 v[92:93], v[122:123], v[168:169] op_sel_hi:[1,0]
	v_pk_mul_f32 v[94:95], v[118:119], v[166:167] op_sel:[0,1]
	v_pk_mul_f32 v[108:109], v[120:121], v[168:169] op_sel_hi:[1,0]
	s_ashr_i32 s7, s12, 31
	s_add_u32 s6, s13, s12
	s_addc_u32 s7, 0, s7
	s_lshl_b64 s[6:7], s[6:7], 6
	s_waitcnt vmcnt(2)
	v_pk_mul_f32 v[122:123], v[32:33], v[68:69] op_sel_hi:[1,0]
	v_mov_b32_e32 v32, v67
	s_waitcnt vmcnt(0)
; #define LAS __attribute__((address_space(3)))
; __device__ __forceinline__ unsigned cvt_pk_bf16(float lo, float hi) { unsigned r; asm volatile("v_cvt_pk_bf16_f32 %0, %1, %2" : "=v"(r) : "v"(lo), "v"(hi)); return r; }
; __device__ __forceinline__ void conv_item(const float* W, int ldw, int Nout, int mode, const float* gk, unsigned char* dst, int item, int lane, LAS unsigned char* wl  ) {
;     ...
;     LAS unsigned char* mine = wl + lane * 272;
; #pragma unroll
;     for (int j = 0; j < 4; ++j)
; #pragma unroll
;         for (int q = 0; q < 4; ++q) { u32x4 w;
;             w.x = cvt_pk_bf16(v[8 * q + 0][j], v[8 * q + 1][j]); w.y = cvt_pk_bf16(v[8 * q + 2][j], v[8 * q + 3][j]);
;             w.z = cvt_pk_bf16(v[8 * q + 4][j], v[8 * q + 5][j]); w.w = cvt_pk_bf16(v[8 * q + 6][j], v[8 * q + 7][j]);
;             *(LAS u32x4*)(mine + (j * 4 + q) * 16) = w; }
;     asm volatile("s_waitcnt lgkmcnt(0)" ::: "memory");
;     unsigned char* d = dst + ((size_t)k32 * Nout + nb0) * 64 + lane * 16;
;     const LAS unsigned char* rd = wl + (lane >> 4) * 272 + (lane & 15) * 16;
; #pragma unroll
;     for (int s = 0; s < 16; ++s) { const u32x4 w = *(const LAS u32x4*)(rd + s * 4 * 272); *(u32x4*)(d + s * 1024) = w; }
;     asm volatile("s_waitcnt lgkmcnt(0)" ::: "memory");
	v_pk_mul_f32 v[116:117], v[8:9], v[78:79] op_sel_hi:[1,0]
	v_mov_b32_e32 v8, v79
	v_pk_mul_f32 v[114:115], v[0:1], v[76:77] op_sel_hi:[1,0]
	v_pk_mul_f32 v[0:1], v[6:7], v[76:77] op_sel:[0,1]
	v_pk_mul_f32 v[6:7], v[14:15], v[8:9] op_sel_hi:[1,0]
	v_mov_b32_e32 v14, v75
	v_pk_mul_f32 v[2:3], v[2:3], v[76:77] op_sel_hi:[1,0]
	v_pk_mul_f32 v[76:77], v[4:5], v[76:77] op_sel:[0,1]
	v_pk_mul_f32 v[4:5], v[10:11], v[78:79] op_sel_hi:[1,0]
	v_pk_mul_f32 v[78:79], v[12:13], v[8:9] op_sel_hi:[1,0]
	v_pk_mul_f32 v[8:9], v[18:19], v[72:73] op_sel_hi:[1,0]
	v_pk_mul_f32 v[118:119], v[16:17], v[72:73] op_sel_hi:[1,0]
	v_pk_mul_f32 v[10:11], v[22:23], v[72:73] op_sel:[0,1]
	v_pk_mul_f32 v[72:73], v[20:21], v[72:73] op_sel:[0,1]
	v_pk_mul_f32 v[12:13], v[26:27], v[74:75] op_sel_hi:[1,0]
	v_pk_mul_f32 v[120:121], v[24:25], v[74:75] op_sel_hi:[1,0]
	v_pk_mul_f32 v[16:17], v[30:31], v[14:15] op_sel_hi:[1,0]
	v_pk_mul_f32 v[74:75], v[28:29], v[14:15] op_sel_hi:[1,0]
	v_pk_mul_f32 v[14:15], v[34:35], v[68:69] op_sel_hi:[1,0]
	v_pk_mul_f32 v[20:21], v[42:43], v[70:71] op_sel_hi:[1,0]
	v_pk_mul_f32 v[42:43], v[48:49], v[64:65] op_sel_hi:[1,0]
	v_pk_mul_f32 v[30:31], v[62:63], v[32:33] op_sel_hi:[1,0]
	v_pk_mul_f32 v[48:49], v[60:61], v[32:33] op_sel_hi:[1,0]
	v_cvt_pk_bf16_f32 v32, v146, v150
	v_cvt_pk_bf16_f32 v33, v148, v154
	v_cvt_pk_bf16_f32 v34, v152, v158
	v_cvt_pk_bf16_f32 v35, v156, v160
	ds_write_b128 v163, v[32:35]
	v_cvt_pk_bf16_f32 v32, v98, v102
	v_cvt_pk_bf16_f32 v33, v100, v106
	v_cvt_pk_bf16_f32 v34, v104, v110
	v_cvt_pk_bf16_f32 v35, v108, v112
	v_mov_b32_e32 v24, v71
	ds_write_b128 v163, v[32:35] offset:16
	v_cvt_pk_bf16_f32 v32, v114, v76
	v_cvt_pk_bf16_f32 v33, v116, v78
	v_cvt_pk_bf16_f32 v34, v118, v72
	v_cvt_pk_bf16_f32 v35, v120, v74
	v_pk_mul_f32 v[18:19], v[38:39], v[68:69] op_sel:[0,1]
	v_pk_mul_f32 v[36:37], v[36:37], v[68:69] op_sel:[0,1]
	v_pk_mul_f32 v[38:39], v[40:41], v[70:71] op_sel_hi:[1,0]
	v_pk_mul_f32 v[22:23], v[46:47], v[24:25] op_sel_hi:[1,0]
	v_pk_mul_f32 v[40:41], v[44:45], v[24:25] op_sel_hi:[1,0]
	v_pk_mul_f32 v[44:45], v[52:53], v[64:65] op_sel:[0,1]
	v_pk_mul_f32 v[46:47], v[56:57], v[66:67] op_sel_hi:[1,0]
	ds_write_b128 v163, v[32:35] offset:32
	v_cvt_pk_bf16_f32 v32, v122, v36
	v_cvt_pk_bf16_f32 v33, v38, v40
	v_cvt_pk_bf16_f32 v34, v42, v44
	v_cvt_pk_bf16_f32 v35, v46, v48
	ds_write_b128 v163, v[32:35] offset:48
	v_cvt_pk_bf16_f32 v32, v147, v151
	v_cvt_pk_bf16_f32 v33, v149, v155
	v_cvt_pk_bf16_f32 v34, v153, v159
	v_cvt_pk_bf16_f32 v35, v157, v161
	ds_write_b128 v163, v[32:35] offset:64
	v_cvt_pk_bf16_f32 v32, v99, v103
	v_cvt_pk_bf16_f32 v33, v101, v107
	v_cvt_pk_bf16_f32 v34, v105, v111
	v_cvt_pk_bf16_f32 v35, v109, v113
	ds_write_b128 v163, v[32:35] offset:80
	v_cvt_pk_bf16_f32 v32, v115, v77
	v_cvt_pk_bf16_f32 v33, v117, v79
	v_cvt_pk_bf16_f32 v34, v119, v73
	v_cvt_pk_bf16_f32 v35, v121, v75
	ds_write_b128 v163, v[32:35] offset:96
	v_cvt_pk_bf16_f32 v32, v123, v37
	v_cvt_pk_bf16_f32 v33, v39, v41
	v_cvt_pk_bf16_f32 v34, v43, v45
	v_cvt_pk_bf16_f32 v35, v47, v49
	ds_write_b128 v163, v[32:35] offset:112
	v_cvt_pk_bf16_f32 v32, v130, v134
	v_cvt_pk_bf16_f32 v33, v132, v140
	v_cvt_pk_bf16_f32 v34, v136, v142
	v_cvt_pk_bf16_f32 v35, v86, v144
	ds_write_b128 v163, v[32:35] offset:128
	v_cvt_pk_bf16_f32 v32, v80, v84
	v_cvt_pk_bf16_f32 v33, v82, v90
	v_cvt_pk_bf16_f32 v34, v88, v94
	v_cvt_pk_bf16_f32 v35, v92, v96
	ds_write_b128 v163, v[32:35] offset:144
	v_cvt_pk_bf16_f32 v32, v2, v0
	v_cvt_pk_bf16_f32 v33, v4, v6
	v_cvt_pk_bf16_f32 v34, v8, v10
	v_cvt_pk_bf16_f32 v35, v12, v16
	v_pk_mul_f32 v[24:25], v[50:51], v[64:65] op_sel_hi:[1,0]
	v_pk_mul_f32 v[26:27], v[54:55], v[64:65] op_sel:[0,1]
	v_pk_mul_f32 v[28:29], v[58:59], v[66:67] op_sel_hi:[1,0]
	ds_write_b128 v163, v[32:35] offset:160
	v_cvt_pk_bf16_f32 v32, v14, v18
	v_cvt_pk_bf16_f32 v33, v20, v22
	v_cvt_pk_bf16_f32 v34, v24, v26
	v_cvt_pk_bf16_f32 v35, v28, v30
	ds_write_b128 v163, v[32:35] offset:176
	v_cvt_pk_bf16_f32 v32, v131, v135
	v_cvt_pk_bf16_f32 v33, v133, v141
	v_cvt_pk_bf16_f32 v34, v137, v143
	v_cvt_pk_bf16_f32 v35, v87, v145
	ds_write_b128 v163, v[32:35] offset:192
	v_cvt_pk_bf16_f32 v32, v81, v85
	v_cvt_pk_bf16_f32 v33, v83, v91
	v_cvt_pk_bf16_f32 v34, v89, v95
	v_cvt_pk_bf16_f32 v35, v93, v97
	ds_write_b128 v163, v[32:35] offset:208
	v_cvt_pk_bf16_f32 v0, v3, v1
	v_cvt_pk_bf16_f32 v1, v5, v7
	v_cvt_pk_bf16_f32 v2, v9, v11
	v_cvt_pk_bf16_f32 v3, v13, v17
	ds_write_b128 v163, v[0:3] offset:224
	v_cvt_pk_bf16_f32 v0, v15, v19
	v_cvt_pk_bf16_f32 v1, v21, v23
	v_cvt_pk_bf16_f32 v2, v25, v27
	v_cvt_pk_bf16_f32 v3, v29, v31
	ds_write_b128 v163, v[0:3] offset:240
	s_waitcnt lgkmcnt(0)
	ds_read_b128 v[0:3], v164
	v_lshl_add_u64 v[4:5], v[128:129], 0, s[6:7]
	v_add_co_u32_e32 v6, vcc, s34, v4
	s_waitcnt lgkmcnt(0)
	global_store_dwordx4 v[4:5], v[0:3], off nt
	ds_read_b128 v[0:3], v164 offset:1088
	v_addc_co_u32_e32 v7, vcc, 0, v5, vcc
	v_add_co_u32_e32 v8, vcc, s60, v4
	s_waitcnt lgkmcnt(0)
	global_store_dwordx4 v[4:5], v[0:3], off offset:1024 nt
	ds_read_b128 v[0:3], v164 offset:2176
	v_addc_co_u32_e32 v9, vcc, 0, v5, vcc
	s_waitcnt lgkmcnt(0)
	global_store_dwordx4 v[4:5], v[0:3], off offset:2048 nt
	ds_read_b128 v[0:3], v164 offset:3264
	s_waitcnt lgkmcnt(0)
	global_store_dwordx4 v[4:5], v[0:3], off offset:3072 nt
	ds_read_b128 v[0:3], v164 offset:4352
	v_add_co_u32_e32 v4, vcc, 0x3000, v4
	s_waitcnt lgkmcnt(0)
	global_store_dwordx4 v[8:9], v[0:3], off offset:-4096 nt
	ds_read_b128 v[0:3], v164 offset:5440
	v_addc_co_u32_e32 v5, vcc, 0, v5, vcc
	s_waitcnt lgkmcnt(0)
	global_store_dwordx4 v[6:7], v[0:3], off offset:1024 nt
	ds_read_b128 v[0:3], v164 offset:6528
	s_waitcnt lgkmcnt(0)
	global_store_dwordx4 v[6:7], v[0:3], off offset:2048 nt
	ds_read_b128 v[0:3], v164 offset:7616
	s_waitcnt lgkmcnt(0)
	global_store_dwordx4 v[6:7], v[0:3], off offset:3072 nt
	ds_read_b128 v[0:3], v164 offset:8704
	s_waitcnt lgkmcnt(0)
	global_store_dwordx4 v[8:9], v[0:3], off nt
	ds_read_b128 v[0:3], v164 offset:9792
	s_waitcnt lgkmcnt(0)
	global_store_dwordx4 v[8:9], v[0:3], off offset:1024 nt
	ds_read_b128 v[0:3], v164 offset:10880
	s_waitcnt lgkmcnt(0)
	global_store_dwordx4 v[8:9], v[0:3], off offset:2048 nt
	ds_read_b128 v[0:3], v164 offset:11968
	s_waitcnt lgkmcnt(0)
	global_store_dwordx4 v[8:9], v[0:3], off offset:3072 nt
	ds_read_b128 v[0:3], v164 offset:13056
	s_waitcnt lgkmcnt(0)
	global_store_dwordx4 v[4:5], v[0:3], off nt
	ds_read_b128 v[0:3], v164 offset:14144
	s_waitcnt lgkmcnt(0)
	global_store_dwordx4 v[4:5], v[0:3], off offset:1024 nt
	ds_read_b128 v[0:3], v164 offset:15232
	s_waitcnt lgkmcnt(0)
	global_store_dwordx4 v[4:5], v[0:3], off offset:2048 nt
	ds_read_b128 v[0:3], v164 offset:16320
	s_waitcnt lgkmcnt(0)
	global_store_dwordx4 v[4:5], v[0:3], off offset:3072 nt
	s_waitcnt lgkmcnt(0)
	s_branch .LBB0_852

; #define LAS __attribute__((address_space(3)))
; __device__ __forceinline__ unsigned cvt_pk_bf16(float lo, float hi) { unsigned r; asm volatile("v_cvt_pk_bf16_f32 %0, %1, %2" : "=v"(r) : "v"(lo), "v"(hi)); return r; }
; __device__ __forceinline__ void conv_item(const float* W, int ldw, int Nout, int mode, const float* gk, unsigned char* dst, int item, int lane, LAS unsigned char* wl  ) {
;     const int nblk = Nout >> 8, k32 = item / nblk, nb0 = (item - k32 * nblk) * 256, nb = nb0 + lane * 4;
;     int sc = nb; if (mode == 1) sc = ((nb >> 7) & 1) * FF + (nb >> 8) * 128 + (nb & 127);
;     const float* src = W + (size_t)(k32 * 32) * ldw + sc;
;     f32x4 v[32];
; #pragma unroll
;     for (int i = 0; i < 32; ++i) v[i] = __builtin_nontemporal_load((const f32x4*)(src + (size_t)i * ldw));
;     if (gk) {
; #pragma unroll
;         for (int i = 0; i < 32; ++i) v[i] *= gk[k32 * 32 + i]; }
;     LAS unsigned char* mine = wl + lane * 272;
; #pragma unroll
;     for (int j = 0; j < 4; ++j)
; #pragma unroll
;         for (int q = 0; q < 4; ++q) { u32x4 w;
;             w.x = cvt_pk_bf16(v[8 * q + 0][j], v[8 * q + 1][j]); w.y = cvt_pk_bf16(v[8 * q + 2][j], v[8 * q + 3][j]);
;             w.z = cvt_pk_bf16(v[8 * q + 4][j], v[8 * q + 5][j]); w.w = cvt_pk_bf16(v[8 * q + 6][j], v[8 * q + 7][j]);
;             *(LAS u32x4*)(mine + (j * 4 + q) * 16) = w; }
.LBB0_858:
	s_cmp_lt_i32 s0, 0
	s_cbranch_scc1 .LBB0_857
	s_lshr_b32 s6, s0, 3
	s_lshl_b32 s24, s6, 11
	s_lshl_b32 s30, s6, 16
	s_sub_i32 s25, s13, s24
	s_lshl_b64 s[6:7], s[30:31], 2
	v_subrev_u32_e32 v0, s24, v130
	s_add_u32 s6, s1, s6
	s_addc_u32 s7, s12, s7
	v_ashrrev_i32_e32 v1, 31, v0
	v_lshl_add_u64 v[120:121], v[0:1], 2, s[6:7]
	v_add_co_u32_e32 v4, vcc, s60, v120
	s_mov_b32 s6, 0x16000
	s_nop 0
	v_addc_co_u32_e32 v5, vcc, 0, v121, vcc
	v_add_co_u32_e32 v8, vcc, s26, v120
	global_load_dwordx4 v[0:3], v[120:121], off nt
	s_nop 0
	global_load_dwordx4 v[4:7], v[4:5], off nt
	v_addc_co_u32_e32 v9, vcc, 0, v121, vcc
	v_add_co_u32_e32 v12, vcc, s62, v120
	s_ashr_i32 s7, s25, 31
	s_nop 0
	v_addc_co_u32_e32 v13, vcc, 0, v121, vcc
	v_add_co_u32_e32 v16, vcc, s27, v120
	global_load_dwordx4 v[8:11], v[8:9], off nt
	s_nop 0
	global_load_dwordx4 v[12:15], v[12:13], off nt
	v_addc_co_u32_e32 v17, vcc, 0, v121, vcc
	v_add_co_u32_e32 v20, vcc, s64, v120
	s_nop 1
	v_addc_co_u32_e32 v21, vcc, 0, v121, vcc
	v_add_co_u32_e32 v24, vcc, s67, v120
	global_load_dwordx4 v[16:19], v[16:17], off nt
	s_nop 0
	global_load_dwordx4 v[20:23], v[20:21], off nt
	v_addc_co_u32_e32 v25, vcc, 0, v121, vcc
	v_add_co_u32_e32 v28, vcc, s11, v120
	s_nop 1
	v_addc_co_u32_e32 v29, vcc, 0, v121, vcc
	v_add_co_u32_e32 v32, vcc, s28, v120
	global_load_dwordx4 v[24:27], v[24:25], off nt
	s_nop 0
	global_load_dwordx4 v[28:31], v[28:29], off nt
	v_addc_co_u32_e32 v33, vcc, 0, v121, vcc
	v_add_co_u32_e32 v36, vcc, s29, v120
	s_nop 1
	v_addc_co_u32_e32 v37, vcc, 0, v121, vcc
	v_add_co_u32_e32 v40, vcc, s38, v120
	global_load_dwordx4 v[32:35], v[32:33], off nt
	s_nop 0
	global_load_dwordx4 v[36:39], v[36:37], off nt
	v_addc_co_u32_e32 v41, vcc, 0, v121, vcc
	v_add_co_u32_e32 v44, vcc, s6, v120
	s_mov_b32 s6, 0x2c000
	s_nop 0
	v_addc_co_u32_e32 v45, vcc, 0, v121, vcc
	v_add_co_u32_e32 v48, vcc, s39, v120
	global_load_dwordx4 v[40:43], v[40:41], off nt
	s_nop 0
	global_load_dwordx4 v[44:47], v[44:45], off nt
	v_addc_co_u32_e32 v49, vcc, 0, v121, vcc
	v_add_co_u32_e32 v52, vcc, s40, v120
	s_nop 1
	v_addc_co_u32_e32 v53, vcc, 0, v121, vcc
	v_add_co_u32_e32 v56, vcc, s41, v120
	global_load_dwordx4 v[48:51], v[48:49], off nt
	s_nop 0
	global_load_dwordx4 v[52:55], v[52:53], off nt
	v_addc_co_u32_e32 v57, vcc, 0, v121, vcc
	v_add_co_u32_e32 v60, vcc, s42, v120
	s_nop 1
	v_addc_co_u32_e32 v61, vcc, 0, v121, vcc
	v_add_co_u32_e32 v64, vcc, s43, v120
	global_load_dwordx4 v[56:59], v[56:57], off nt
	s_nop 0
	global_load_dwordx4 v[60:63], v[60:61], off nt
	v_addc_co_u32_e32 v65, vcc, 0, v121, vcc
	v_add_co_u32_e32 v68, vcc, s44, v120
	s_nop 1
	v_addc_co_u32_e32 v69, vcc, 0, v121, vcc
	v_add_co_u32_e32 v72, vcc, s45, v120
	global_load_dwordx4 v[64:67], v[64:65], off nt
	s_nop 0
	global_load_dwordx4 v[68:71], v[68:69], off nt
	v_addc_co_u32_e32 v73, vcc, 0, v121, vcc
	v_add_co_u32_e32 v76, vcc, s46, v120
	s_nop 1
	v_addc_co_u32_e32 v77, vcc, 0, v121, vcc
	v_add_co_u32_e32 v80, vcc, s47, v120
	global_load_dwordx4 v[72:75], v[72:73], off nt
	s_nop 0
	global_load_dwordx4 v[76:79], v[76:77], off nt
	v_addc_co_u32_e32 v81, vcc, 0, v121, vcc
	v_add_co_u32_e32 v84, vcc, s48, v120
	s_nop 1
	v_addc_co_u32_e32 v85, vcc, 0, v121, vcc
	v_add_co_u32_e32 v88, vcc, s6, v120
	global_load_dwordx4 v[80:83], v[80:81], off nt
	s_nop 0
	global_load_dwordx4 v[84:87], v[84:85], off nt
	v_addc_co_u32_e32 v89, vcc, 0, v121, vcc
	v_add_co_u32_e32 v92, vcc, s49, v120
	s_add_u32 s6, s25, s24
	s_nop 0
	v_addc_co_u32_e32 v93, vcc, 0, v121, vcc
	v_add_co_u32_e32 v96, vcc, s50, v120
	global_load_dwordx4 v[88:91], v[88:89], off nt
	s_nop 0
	global_load_dwordx4 v[92:95], v[92:93], off nt
	v_addc_co_u32_e32 v97, vcc, 0, v121, vcc
	v_add_co_u32_e32 v100, vcc, s51, v120
	s_addc_u32 s7, s7, 0
	s_nop 0
	v_addc_co_u32_e32 v101, vcc, 0, v121, vcc
	v_add_co_u32_e32 v104, vcc, s52, v120
	global_load_dwordx4 v[96:99], v[96:97], off nt
	s_nop 0
	global_load_dwordx4 v[100:103], v[100:101], off nt
	v_addc_co_u32_e32 v105, vcc, 0, v121, vcc
	v_add_co_u32_e32 v108, vcc, s53, v120
	s_lshl_b64 s[6:7], s[6:7], 6
	s_nop 0
	v_addc_co_u32_e32 v109, vcc, 0, v121, vcc
	v_add_co_u32_e32 v112, vcc, s54, v120
	global_load_dwordx4 v[104:107], v[104:105], off nt
	s_nop 0
	global_load_dwordx4 v[108:111], v[108:109], off nt
	v_addc_co_u32_e32 v113, vcc, 0, v121, vcc
	v_add_co_u32_e32 v116, vcc, s55, v120
	s_nop 1
	v_addc_co_u32_e32 v117, vcc, 0, v121, vcc
	v_add_co_u32_e32 v122, vcc, s56, v120
	global_load_dwordx4 v[112:115], v[112:113], off nt
	s_nop 0
	global_load_dwordx4 v[116:119], v[116:117], off nt
	v_addc_co_u32_e32 v123, vcc, 0, v121, vcc
	v_add_co_u32_e32 v124, vcc, s57, v120
	s_nop 1
	v_addc_co_u32_e32 v125, vcc, 0, v121, vcc
	global_load_dwordx4 v[120:123], v[122:123], off nt
	s_nop 0
	global_load_dwordx4 v[124:127], v[124:125], off nt
	s_waitcnt vmcnt(30)
	v_cvt_pk_bf16_f32 v134, v0, v4
	s_waitcnt vmcnt(28)
	v_cvt_pk_bf16_f32 v135, v8, v12
	s_waitcnt vmcnt(26)
	v_cvt_pk_bf16_f32 v136, v16, v20
	s_waitcnt vmcnt(24)
	v_cvt_pk_bf16_f32 v137, v24, v28
	ds_write_b128 v131, v[134:137]
	s_waitcnt vmcnt(22)
	v_cvt_pk_bf16_f32 v134, v32, v36
	s_waitcnt vmcnt(20)
; #define LAS __attribute__((address_space(3)))
; __device__ __forceinline__ unsigned cvt_pk_bf16(float lo, float hi) { unsigned r; asm volatile("v_cvt_pk_bf16_f32 %0, %1, %2" : "=v"(r) : "v"(lo), "v"(hi)); return r; }
; __device__ __forceinline__ void conv_item(const float* W, int ldw, int Nout, int mode, const float* gk, unsigned char* dst, int item, int lane, LAS unsigned char* wl  ) {
;     ...
;         for (int q = 0; q < 4; ++q) { u32x4 w;
;             w.x = cvt_pk_bf16(v[8 * q + 0][j], v[8 * q + 1][j]); w.y = cvt_pk_bf16(v[8 * q + 2][j], v[8 * q + 3][j]);
;             w.z = cvt_pk_bf16(v[8 * q + 4][j], v[8 * q + 5][j]); w.w = cvt_pk_bf16(v[8 * q + 6][j], v[8 * q + 7][j]);
;             *(LAS u32x4*)(mine + (j * 4 + q) * 16) = w; }
;     asm volatile("s_waitcnt lgkmcnt(0)" ::: "memory");
;     unsigned char* d = dst + ((size_t)k32 * Nout + nb0) * 64 + lane * 16;
;     const LAS unsigned char* rd = wl + (lane >> 4) * 272 + (lane & 15) * 16;
; #pragma unroll
;     for (int s = 0; s < 16; ++s) { const u32x4 w = *(const LAS u32x4*)(rd + s * 4 * 272); *(u32x4*)(d + s * 1024) = w; }
;     asm volatile("s_waitcnt lgkmcnt(0)" ::: "memory");
	v_cvt_pk_bf16_f32 v135, v40, v44
	s_waitcnt vmcnt(18)
	v_cvt_pk_bf16_f32 v136, v48, v52
	s_waitcnt vmcnt(16)
	v_cvt_pk_bf16_f32 v137, v56, v60
	ds_write_b128 v131, v[134:137] offset:16
	s_waitcnt vmcnt(14)
	v_cvt_pk_bf16_f32 v134, v64, v68
	s_waitcnt vmcnt(12)
	v_cvt_pk_bf16_f32 v135, v72, v76
	s_waitcnt vmcnt(10)
	v_cvt_pk_bf16_f32 v136, v80, v84
	s_waitcnt vmcnt(8)
	v_cvt_pk_bf16_f32 v137, v88, v92
	ds_write_b128 v131, v[134:137] offset:32
	s_waitcnt vmcnt(6)
	v_cvt_pk_bf16_f32 v134, v96, v100
	s_waitcnt vmcnt(4)
	v_cvt_pk_bf16_f32 v135, v104, v108
	s_waitcnt vmcnt(2)
	v_cvt_pk_bf16_f32 v136, v112, v116
	s_waitcnt vmcnt(0)
	v_cvt_pk_bf16_f32 v137, v120, v124
	ds_write_b128 v131, v[134:137] offset:48
	v_cvt_pk_bf16_f32 v134, v1, v5
	v_cvt_pk_bf16_f32 v135, v9, v13
	v_cvt_pk_bf16_f32 v136, v17, v21
	v_cvt_pk_bf16_f32 v137, v25, v29
	ds_write_b128 v131, v[134:137] offset:64
	v_cvt_pk_bf16_f32 v134, v33, v37
	v_cvt_pk_bf16_f32 v135, v41, v45
	v_cvt_pk_bf16_f32 v136, v49, v53
	v_cvt_pk_bf16_f32 v137, v57, v61
	ds_write_b128 v131, v[134:137] offset:80
	v_cvt_pk_bf16_f32 v134, v65, v69
	v_cvt_pk_bf16_f32 v135, v73, v77
	v_cvt_pk_bf16_f32 v136, v81, v85
	v_cvt_pk_bf16_f32 v137, v89, v93
	ds_write_b128 v131, v[134:137] offset:96
	v_cvt_pk_bf16_f32 v134, v97, v101
	v_cvt_pk_bf16_f32 v135, v105, v109
	v_cvt_pk_bf16_f32 v136, v113, v117
	v_cvt_pk_bf16_f32 v137, v121, v125
	ds_write_b128 v131, v[134:137] offset:112
	v_cvt_pk_bf16_f32 v134, v2, v6
	v_cvt_pk_bf16_f32 v135, v10, v14
	v_cvt_pk_bf16_f32 v136, v18, v22
	v_cvt_pk_bf16_f32 v137, v26, v30
	ds_write_b128 v131, v[134:137] offset:128
	v_cvt_pk_bf16_f32 v134, v34, v38
	v_cvt_pk_bf16_f32 v135, v42, v46
	v_cvt_pk_bf16_f32 v136, v50, v54
	v_cvt_pk_bf16_f32 v137, v58, v62
	ds_write_b128 v131, v[134:137] offset:144
	v_cvt_pk_bf16_f32 v134, v66, v70
	v_cvt_pk_bf16_f32 v135, v74, v78
	v_cvt_pk_bf16_f32 v136, v82, v86
	v_cvt_pk_bf16_f32 v137, v90, v94
	ds_write_b128 v131, v[134:137] offset:160
	v_cvt_pk_bf16_f32 v134, v98, v102
	v_cvt_pk_bf16_f32 v135, v106, v110
	v_cvt_pk_bf16_f32 v136, v114, v118
	v_cvt_pk_bf16_f32 v137, v122, v126
	ds_write_b128 v131, v[134:137] offset:176
	v_cvt_pk_bf16_f32 v0, v3, v7
	v_cvt_pk_bf16_f32 v1, v11, v15
	v_cvt_pk_bf16_f32 v2, v19, v23
	v_cvt_pk_bf16_f32 v3, v27, v31
	ds_write_b128 v131, v[0:3] offset:192
	v_cvt_pk_bf16_f32 v0, v35, v39
	v_cvt_pk_bf16_f32 v1, v43, v47
	v_cvt_pk_bf16_f32 v2, v51, v55
	v_cvt_pk_bf16_f32 v3, v59, v63
	ds_write_b128 v131, v[0:3] offset:208
	v_cvt_pk_bf16_f32 v0, v67, v71
	v_cvt_pk_bf16_f32 v1, v75, v79
	v_cvt_pk_bf16_f32 v2, v83, v87
	v_cvt_pk_bf16_f32 v3, v91, v95
	ds_write_b128 v131, v[0:3] offset:224
	v_cvt_pk_bf16_f32 v0, v99, v103
	v_cvt_pk_bf16_f32 v1, v107, v111
	v_cvt_pk_bf16_f32 v2, v115, v119
	v_cvt_pk_bf16_f32 v3, v123, v127
	ds_write_b128 v131, v[0:3] offset:240
	s_waitcnt lgkmcnt(0)
	ds_read_b128 v[0:3], v132
	ds_read_b128 v[4:7], v132 offset:1088
	ds_read_b128 v[8:11], v132 offset:2176
	ds_read_b128 v[12:15], v132 offset:3264
	v_lshl_add_u64 v[20:21], v[128:129], 0, s[6:7]
	s_waitcnt lgkmcnt(3)
	global_store_dwordx4 v[20:21], v[0:3], off nt
	s_waitcnt lgkmcnt(2)
	global_store_dwordx4 v[20:21], v[4:7], off offset:1024 nt
	s_waitcnt lgkmcnt(1)
	global_store_dwordx4 v[20:21], v[8:11], off offset:2048 nt
	s_waitcnt lgkmcnt(0)
	global_store_dwordx4 v[20:21], v[12:15], off offset:3072 nt
	ds_read_b128 v[0:3], v132 offset:4352
	ds_read_b128 v[4:7], v132 offset:5440
	ds_read_b128 v[8:11], v132 offset:6528
	v_add_co_u32_e32 v22, vcc, s34, v20
	s_nop 1
	v_addc_co_u32_e32 v23, vcc, 0, v21, vcc
	v_add_co_u32_e32 v24, vcc, s60, v20
	s_nop 1
	v_addc_co_u32_e32 v25, vcc, 0, v21, vcc
	s_waitcnt lgkmcnt(2)
	global_store_dwordx4 v[24:25], v[0:3], off offset:-4096 nt
	s_waitcnt lgkmcnt(1)
	global_store_dwordx4 v[22:23], v[4:7], off offset:1024 nt
	s_waitcnt lgkmcnt(0)
	global_store_dwordx4 v[22:23], v[8:11], off offset:2048 nt
	ds_read_b128 v[0:3], v132 offset:7616
	ds_read_b128 v[4:7], v132 offset:8704
	ds_read_b128 v[8:11], v132 offset:9792
	ds_read_b128 v[12:15], v132 offset:10880
	ds_read_b128 v[16:19], v132 offset:11968
	s_waitcnt lgkmcnt(4)
	global_store_dwordx4 v[22:23], v[0:3], off offset:3072 nt
	s_waitcnt lgkmcnt(3)
	global_store_dwordx4 v[24:25], v[4:7], off nt
	s_waitcnt lgkmcnt(2)
	global_store_dwordx4 v[24:25], v[8:11], off offset:1024 nt
	s_waitcnt lgkmcnt(1)
	global_store_dwordx4 v[24:25], v[12:15], off offset:2048 nt
	s_waitcnt lgkmcnt(0)
	global_store_dwordx4 v[24:25], v[16:19], off offset:3072 nt
	ds_read_b128 v[0:3], v132 offset:13056
	ds_read_b128 v[4:7], v132 offset:14144
	ds_read_b128 v[8:11], v132 offset:15232
	ds_read_b128 v[12:15], v132 offset:16320
	v_add_co_u32_e32 v16, vcc, 0x3000, v20
	s_nop 1
	v_addc_co_u32_e32 v17, vcc, 0, v21, vcc
	s_waitcnt lgkmcnt(3)
	global_store_dwordx4 v[16:17], v[0:3], off nt
	s_waitcnt lgkmcnt(2)
	global_store_dwordx4 v[16:17], v[4:7], off offset:1024 nt
	s_waitcnt lgkmcnt(1)
	global_store_dwordx4 v[16:17], v[8:11], off offset:2048 nt
	s_waitcnt lgkmcnt(0)
	global_store_dwordx4 v[16:17], v[12:15], off offset:3072 nt
	s_waitcnt lgkmcnt(0)
	s_branch .LBB0_857
